# v97 + GEMM K-loop back-edge rotation (stack of GELU/SwiGLU constant regrouping and loop-edge rotation)
# baseline (speedup 1.0000x reference)
; #define ROWS8 _Pragma("unroll") for (int ai = 0; ai < 2; ++ai) _Pragma("unroll") for (int m = 0; m < 4; ++m) if (ai == 0 || !hf)
; #define PK8(v0, v1) ({ const u32x2 h0_ = pk4(v0), h1_ = pk4(v1); (u32x4){h0_.x, h0_.y, h1_.x, h1_.y}; })
; #define LOAD_COLP_RS(rsc, ssqp, invn) f32x4 rsc[2][2]; COLS4 rsc[bj][n] = *(const f32x4*)((ssqp) + colp + bj * HALF + n * 4); \
;         COLS4 rsc[bj][n] = (f32x4){rstd_of(rsc[bj][n][0], invn), rstd_of(rsc[bj][n][1], invn), rstd_of(rsc[bj][n][2], invn), rstd_of(rsc[bj][n][3], invn)}
; DI float gelu_tanh(float x) { const float t = x * (1.5957691216f + 0.0713548163f * x * x); return x * __builtin_amdgcn_rcpf(1.f + __builtin_amdgcn_exp2f(-1.4426950409f * t)); }
;     DI void operator()(const Acc& acc, const Unit& u, int wr, int wc, int fr, int fq) const {
;     ...
;                 float* ssqv = SSQ(1 + sqo);
;                 LOAD_COLP_RS(rsc, SSQ(0), 1.f / 2048.f);
; #pragma unroll
;                 for (int bj = 0; bj < 2; ++bj) { const int cc = colp + bj * HALF;
;                     f32x4 sq0 = {0.f, 0.f, 0.f, 0.f}, sq1 = {0.f, 0.f, 0.f, 0.f};
;                     ROWS8 { const int r = row0 + ai * HALF + m * 16; f32x4 v0 = acc[ai][bj][m][0] * rsc[bj][0], v1 = acc[ai][bj][m][1] * rsc[bj][1];
;                         v0[0] = gelu_tanh(v0[0]); v0[1] = gelu_tanh(v0[1]); v0[2] = gelu_tanh(v0[2]); v0[3] = gelu_tanh(v0[3]);
;                         v1[0] = gelu_tanh(v1[0]); v1[1] = gelu_tanh(v1[1]); v1[2] = gelu_tanh(v1[2]); v1[3] = gelu_tanh(v1[3]);
;                         sq0 += v0 * v0; sq1 += v1 * v1; *(u32x4*)(WSB(OFF_VT) + (size_t)r * 8192 + cc) = PK8(v0, v1); }
; #pragma unroll
;                     for (int j = 0; j < 8; ++j) { float t = j < 4 ? sq0[j & 3] : sq1[j & 3];
;                         t += __shfl_xor(t, 1); t += __shfl_xor(t, 2); t += __shfl_xor(t, 4); t += __shfl_xor(t, 8);
;                         if (fr == 0) unsafeAtomicAdd(ssqv + cc + j, t); }
.Lkrot_0_exit:
	s_barrier
.Lpeel_0_exit:
	v_lshl_add_u32 v158, s4, 8, v223
	v_lshl_add_u32 v156, s73, 8, v225
	v_or_b32_e32 v164, 16, v158
	v_or_b32_e32 v162, 32, v158
	v_or_b32_e32 v160, 48, v158
	s_cmp_lg_u32 s74, 0
	v_ashrrev_i32_e32 v157, 31, v156
	v_ashrrev_i32_e32 v159, 31, v158
	v_ashrrev_i32_e32 v165, 31, v164
	v_ashrrev_i32_e32 v163, 31, v162
	v_ashrrev_i32_e32 v161, 31, v160
	s_cbranch_scc0 .LBB0_362
	v_lshlrev_b64 v[136:137], 2, v[156:157]
	v_lshl_add_u64 v[132:133], s[16:17], 0, v[136:137]
	global_load_dwordx4 v[166:169], v[132:133], off
	global_load_dwordx4 v[172:175], v[132:133], off offset:16
	v_lshlrev_b64 v[128:129], 14, v[158:159]
	v_lshlrev_b64 v[170:171], 1, v[156:157]
	v_lshl_add_u64 v[138:139], s[20:21], 0, v[128:129]
	v_lshl_add_u64 v[138:139], v[138:139], 0, v[170:171]
	global_load_dwordx4 v[128:131], v[132:133], off offset:528
	s_nop 0
	global_load_dwordx4 v[132:135], v[132:133], off offset:512
	v_lshl_add_u64 v[136:137], s[18:19], 0, v[136:137]
	s_waitcnt vmcnt(0)
	v_fmamk_f32 v166, v166, 0x3a000000, v233
	v_fmamk_f32 v167, v167, 0x3a000000, v233
	v_fmamk_f32 v168, v168, 0x3a000000, v233
	v_fmamk_f32 v169, v169, 0x3a000000, v233
	v_rsq_f32_e32 v190, v166
	v_rsq_f32_e32 v191, v167
	v_rsq_f32_e32 v186, v168
	v_rsq_f32_e32 v187, v169
	v_fmamk_f32 v172, v172, 0x3a000000, v233
	v_fmamk_f32 v173, v173, 0x3a000000, v233
	v_fmamk_f32 v174, v174, 0x3a000000, v233
	v_fmamk_f32 v175, v175, 0x3a000000, v233
	v_rsq_f32_e32 v182, v172
	v_rsq_f32_e32 v184, v174
	v_rsq_f32_e32 v185, v175
	v_rsq_f32_e32 v183, v173
	v_pk_mul_f32 v[168:169], v[124:125], v[190:191]
	v_pk_mul_f32 v[166:167], v[126:127], v[186:187]
	v_mul_f32_e32 v178, 0xbdd2d3e7, v168
	v_mul_f32_e32 v179, 0xbdd2d3e7, v169
	v_mul_f32_e32 v192, 0xbdd2d3e7, v166
	v_mul_f32_e32 v193, 0xbdd2d3e7, v167
	v_fmaak_f32 v178, v168, v178, 0xc0135761
	v_fmaak_f32 v179, v169, v179, 0xc0135761
	v_pk_mul_f32 v[172:173], v[122:123], v[184:185]
	v_pk_mul_f32 v[174:175], v[120:121], v[182:183]
	v_fmaak_f32 v192, v166, v192, 0xc0135761
	v_fmaak_f32 v193, v167, v193, 0xc0135761
	v_mul_f32_e32 v178, v168, v178
	v_mul_f32_e32 v179, v169, v179
	v_mul_f32_e32 v196, 0xbdd2d3e7, v174
	v_mul_f32_e32 v197, 0xbdd2d3e7, v175
	v_mul_f32_e32 v198, 0xbdd2d3e7, v172
	v_mul_f32_e32 v199, 0xbdd2d3e7, v173
	v_mul_f32_e32 v192, v166, v192
	v_mul_f32_e32 v193, v167, v193
	v_fmaak_f32 v196, v174, v196, 0xc0135761
	v_fmaak_f32 v197, v175, v197, 0xc0135761
	v_fmaak_f32 v198, v172, v198, 0xc0135761
	v_fmaak_f32 v199, v173, v199, 0xc0135761
	v_exp_f32_e32 v178, v178
	v_exp_f32_e32 v179, v179
	v_mul_f32_e32 v196, v174, v196
	v_mul_f32_e32 v197, v175, v197
	v_mul_f32_e32 v198, v172, v198
	v_mul_f32_e32 v199, v173, v199
	v_exp_f32_e32 v192, v192
	v_exp_f32_e32 v193, v193
	v_exp_f32_e32 v196, v196
	v_exp_f32_e32 v197, v197
	v_exp_f32_e32 v198, v198
	v_exp_f32_e32 v199, v199
	v_add_f32_e32 v178, 1.0, v178
	v_add_f32_e32 v179, 1.0, v179
	v_add_f32_e32 v201, 1.0, v192
	v_add_f32_e32 v202, 1.0, v193
	v_rcp_f32_e32 v192, v178
	v_rcp_f32_e32 v193, v179
	v_add_f32_e32 v196, 1.0, v196
	v_add_f32_e32 v197, 1.0, v197
	v_add_f32_e32 v198, 1.0, v198
	v_add_f32_e32 v199, 1.0, v199
	v_pk_mul_f32 v[194:195], v[104:105], v[182:183]
	v_rcp_f32_e32 v178, v201
	v_rcp_f32_e32 v179, v202
	v_rcp_f32_e32 v196, v196
	v_rcp_f32_e32 v198, v198
	v_rcp_f32_e32 v199, v199
	v_rcp_f32_e32 v197, v197
	v_pk_mul_f32 v[202:203], v[168:169], v[192:193]
	v_mul_f32_e32 v192, 0xbdd2d3e7, v194
	v_fmaak_f32 v192, v194, v192, 0xc0135761
	v_mul_f32_e32 v192, v194, v192
	v_pk_mul_f32 v[178:179], v[166:167], v[178:179]
	v_pk_mul_f32 v[172:173], v[172:173], v[198:199]
	v_pk_mul_f32 v[174:175], v[174:175], v[196:197]
	v_pk_mul_f32 v[176:177], v[110:111], v[186:187]
	v_pk_mul_f32 v[188:189], v[106:107], v[184:185]
	v_cvt_pk_bf16_f32 v166, v202, v203
	v_cvt_pk_bf16_f32 v167, v178, v179
	v_cvt_pk_bf16_f32 v168, v174, v175
	v_cvt_pk_bf16_f32 v169, v172, v173
	v_exp_f32_e32 v192, v192
	global_store_dwordx4 v[138:139], v[166:169], off
	v_mul_f32_e32 v193, 0xbdd2d3e7, v188
	v_fmaak_f32 v193, v188, v193, 0xc0135761
	v_mul_f32_e32 v168, 0xbdd2d3e7, v176
	v_mul_f32_e32 v169, 0xbdd2d3e7, v177
	v_fmaak_f32 v168, v176, v168, 0xc0135761
	v_fmaak_f32 v169, v177, v169, 0xc0135761
	v_mul_f32_e32 v197, 0xbdd2d3e7, v189
	v_mul_f32_e32 v168, v176, v168
	v_mul_f32_e32 v169, v177, v169
	v_mul_f32_e32 v193, v188, v193
	v_fmaak_f32 v197, v189, v197, 0xc0135761
	v_add_f32_e32 v192, 1.0, v192
	v_mul_f32_e32 v197, v189, v197
	v_exp_f32_e32 v168, v168
	v_exp_f32_e32 v169, v169
	v_rcp_f32_e32 v196, v192
	v_mul_f32_e32 v192, 0xbdd2d3e7, v195
	v_exp_f32_e32 v193, v193
	v_fmaak_f32 v192, v195, v192, 0xc0135761
	v_exp_f32_e32 v197, v197
	v_mul_f32_e32 v192, v195, v192
	v_add_f32_e32 v168, 1.0, v168
	v_add_f32_e32 v169, 1.0, v169
	v_exp_f32_e32 v192, v192
	v_add_f32_e32 v193, 1.0, v193
	v_pk_mul_f32 v[180:181], v[108:109], v[190:191]
	v_rcp_f32_e32 v168, v168
	v_rcp_f32_e32 v169, v169
	v_rcp_f32_e32 v198, v193
	v_add_f32_e32 v193, 1.0, v197
	v_mul_f32_e32 v200, 0xbdd2d3e7, v180
	v_mul_f32_e32 v167, 0xbdd2d3e7, v181
	v_rcp_f32_e32 v199, v193
	v_fmaak_f32 v200, v180, v200, 0xc0135761
	v_fmaak_f32 v167, v181, v167, 0xc0135761
	v_mul_f32_e32 v200, v180, v200
	v_mul_f32_e32 v167, v181, v167
	v_add_f32_e32 v192, 1.0, v192
	v_rcp_f32_e32 v197, v192
	v_pk_mul_f32 v[192:193], v[176:177], v[168:169]
	v_pk_mul_f32 v[168:169], v[92:93], v[190:191]
	v_exp_f32_e32 v200, v200
	v_exp_f32_e32 v167, v167
	v_pk_mul_f32 v[176:177], v[188:189], v[198:199]
	v_mul_f32_e32 v188, 0xbdd2d3e7, v168
	v_fmaak_f32 v188, v168, v188, 0xc0135761
	v_mul_f32_e32 v188, v168, v188
	v_add_f32_e32 v166, 1.0, v200
; DI float gelu_tanh(float x) { const float t = x * (1.5957691216f + 0.0713548163f * x * x); return x * __builtin_amdgcn_rcpf(1.f + __builtin_amdgcn_exp2f(-1.4426950409f * t)); }
; #define ROWS8 _Pragma("unroll") for (int ai = 0; ai < 2; ++ai) _Pragma("unroll") for (int m = 0; m < 4; ++m) if (ai == 0 || !hf)
; #define PK8(v0, v1) ({ const u32x2 h0_ = pk4(v0), h1_ = pk4(v1); (u32x4){h0_.x, h0_.y, h1_.x, h1_.y}; })
;     DI void operator()(const Acc& acc, const Unit& u, int wr, int wc, int fr, int fq) const {
;     ...
;                 for (int bj = 0; bj < 2; ++bj) { const int cc = colp + bj * HALF;
;                     f32x4 sq0 = {0.f, 0.f, 0.f, 0.f}, sq1 = {0.f, 0.f, 0.f, 0.f};
;                     ROWS8 { const int r = row0 + ai * HALF + m * 16; f32x4 v0 = acc[ai][bj][m][0] * rsc[bj][0], v1 = acc[ai][bj][m][1] * rsc[bj][1];
;                         v0[0] = gelu_tanh(v0[0]); v0[1] = gelu_tanh(v0[1]); v0[2] = gelu_tanh(v0[2]); v0[3] = gelu_tanh(v0[3]);
;                         v1[0] = gelu_tanh(v1[0]); v1[1] = gelu_tanh(v1[1]); v1[2] = gelu_tanh(v1[2]); v1[3] = gelu_tanh(v1[3]);
;                         sq0 += v0 * v0; sq1 += v1 * v1; *(u32x4*)(WSB(OFF_VT) + (size_t)r * 8192 + cc) = PK8(v0, v1); }
; #pragma unroll
;                     for (int j = 0; j < 8; ++j) { float t = j < 4 ? sq0[j & 3] : sq1[j & 3];
;                         t += __shfl_xor(t, 1); t += __shfl_xor(t, 2); t += __shfl_xor(t, 4); t += __shfl_xor(t, 8);
;                         if (fr == 0) unsafeAtomicAdd(ssqv + cc + j, t); }
	v_add_f32_e32 v167, 1.0, v167
	v_exp_f32_e32 v198, v188
	v_pk_mul_f32 v[188:189], v[94:95], v[186:187]
	v_mul_f32_e32 v199, 0xbdd2d3e7, v169
	v_rcp_f32_e32 v166, v166
	v_rcp_f32_e32 v167, v167
	v_fmaak_f32 v199, v169, v199, 0xc0135761
	v_mul_f32_e32 v200, 0xbdd2d3e7, v188
	v_mul_f32_e32 v199, v169, v199
	v_fmaak_f32 v200, v188, v200, 0xc0135761
	v_mul_f32_e32 v200, v188, v200
	v_exp_f32_e32 v199, v199
	v_pk_mul_f32 v[210:211], v[180:181], v[166:167]
	v_lshlrev_b64 v[166:167], 14, v[164:165]
	v_exp_f32_e32 v204, v200
	v_pk_mul_f32 v[180:181], v[194:195], v[196:197]
	v_lshl_add_u64 v[166:167], s[20:21], 0, v[166:167]
	v_cvt_pk_bf16_f32 v194, v210, v211
	v_cvt_pk_bf16_f32 v195, v192, v193
	v_cvt_pk_bf16_f32 v196, v180, v181
	v_cvt_pk_bf16_f32 v197, v176, v177
	v_lshl_add_u64 v[166:167], v[166:167], 0, v[170:171]
	v_add_f32_e32 v198, 1.0, v198
	global_store_dwordx4 v[166:167], v[194:197], off
	v_rcp_f32_e32 v200, v198
	v_add_f32_e32 v198, 1.0, v199
	v_pk_mul_f32 v[194:195], v[90:91], v[184:185]
	v_pk_mul_f32 v[196:197], v[88:89], v[182:183]
	v_rcp_f32_e32 v201, v198
	v_add_f32_e32 v198, 1.0, v204
	v_mul_f32_e32 v199, 0xbdd2d3e7, v189
	v_mul_f32_e32 v204, 0xbdd2d3e7, v196
	v_mul_f32_e32 v205, 0xbdd2d3e7, v197
	v_mul_f32_e32 v206, 0xbdd2d3e7, v194
	v_mul_f32_e32 v207, 0xbdd2d3e7, v195
	v_fmaak_f32 v199, v189, v199, 0xc0135761
	v_fmaak_f32 v204, v196, v204, 0xc0135761
	v_fmaak_f32 v205, v197, v205, 0xc0135761
	v_fmaak_f32 v206, v194, v206, 0xc0135761
	v_fmaak_f32 v207, v195, v207, 0xc0135761
	v_mul_f32_e32 v199, v189, v199
	v_mul_f32_e32 v204, v196, v204
	v_mul_f32_e32 v205, v197, v205
	v_mul_f32_e32 v206, v194, v206
	v_mul_f32_e32 v207, v195, v207
	v_exp_f32_e32 v199, v199
	v_exp_f32_e32 v204, v204
	v_exp_f32_e32 v205, v205
	v_exp_f32_e32 v206, v206
	v_exp_f32_e32 v207, v207
	v_add_f32_e32 v199, 1.0, v199
	v_add_f32_e32 v204, 1.0, v204
	v_add_f32_e32 v205, 1.0, v205
	v_add_f32_e32 v206, 1.0, v206
	v_add_f32_e32 v207, 1.0, v207
	v_rcp_f32_e32 v198, v198
	v_rcp_f32_e32 v199, v199
	v_rcp_f32_e32 v204, v204
	v_rcp_f32_e32 v206, v206
	v_rcp_f32_e32 v207, v207
	v_rcp_f32_e32 v205, v205
	v_pk_mul_f32 v[198:199], v[188:189], v[198:199]
	v_pk_mul_f32 v[212:213], v[168:169], v[200:201]
	v_pk_mul_f32 v[188:189], v[194:195], v[206:207]
	v_pk_mul_f32 v[194:195], v[196:197], v[204:205]
	v_pk_mul_f32 v[196:197], v[76:77], v[190:191]
	v_lshlrev_b64 v[168:169], 14, v[162:163]
	v_mul_f32_e32 v200, 0xbdd2d3e7, v196
	v_fmaak_f32 v200, v196, v200, 0xc0135761
	v_lshl_add_u64 v[168:169], s[20:21], 0, v[168:169]
	v_mul_f32_e32 v200, v196, v200
	v_cvt_pk_bf16_f32 v204, v212, v213
	v_cvt_pk_bf16_f32 v205, v198, v199
	v_cvt_pk_bf16_f32 v206, v194, v195
	v_cvt_pk_bf16_f32 v207, v188, v189
	v_lshl_add_u64 v[168:169], v[168:169], 0, v[170:171]
	global_store_dwordx4 v[168:169], v[204:207], off
	v_pk_mul_f32 v[208:209], v[72:73], v[182:183]
	s_nop 0
	v_exp_f32_e32 v204, v200
	v_pk_mul_f32 v[200:201], v[78:79], v[186:187]
	v_mul_f32_e32 v205, 0xbdd2d3e7, v197
	v_fmaak_f32 v205, v197, v205, 0xc0135761
	v_mul_f32_e32 v214, 0xbdd2d3e7, v200
	v_mul_f32_e32 v205, v197, v205
	v_fmaak_f32 v214, v200, v214, 0xc0135761
	v_mul_f32_e32 v214, v200, v214
	v_exp_f32_e32 v205, v205
	v_exp_f32_e32 v216, v214
	v_add_f32_e32 v204, 1.0, v204
	v_rcp_f32_e32 v214, v204
	v_add_f32_e32 v204, 1.0, v205
	v_pk_mul_f32 v[206:207], v[74:75], v[184:185]
	v_rcp_f32_e32 v215, v204
	v_add_f32_e32 v204, 1.0, v216
	v_mul_f32_e32 v205, 0xbdd2d3e7, v201
	v_mul_f32_e32 v216, 0xbdd2d3e7, v208
	v_mul_f32_e32 v217, 0xbdd2d3e7, v209
	v_fmaak_f32 v205, v201, v205, 0xc0135761
	v_fmaak_f32 v216, v208, v216, 0xc0135761
	v_fmaak_f32 v217, v209, v217, 0xc0135761
	v_mul_f32_e32 v218, 0xbdd2d3e7, v206
	v_mul_f32_e32 v219, 0xbdd2d3e7, v207
	v_mul_f32_e32 v205, v201, v205
	v_mul_f32_e32 v216, v208, v216
	v_mul_f32_e32 v217, v209, v217
	v_fmaak_f32 v218, v206, v218, 0xc0135761
	v_fmaak_f32 v219, v207, v219, 0xc0135761
	v_mul_f32_e32 v218, v206, v218
	v_mul_f32_e32 v219, v207, v219
	v_exp_f32_e32 v205, v205
	v_exp_f32_e32 v216, v216
	v_exp_f32_e32 v217, v217
	v_exp_f32_e32 v218, v218
	v_exp_f32_e32 v219, v219
	v_add_f32_e32 v205, 1.0, v205
	v_add_f32_e32 v216, 1.0, v216
	v_add_f32_e32 v217, 1.0, v217
	v_rcp_f32_e32 v204, v204
	v_rcp_f32_e32 v205, v205
	v_rcp_f32_e32 v216, v216
	v_add_f32_e32 v218, 1.0, v218
	v_add_f32_e32 v219, 1.0, v219
	v_rcp_f32_e32 v217, v217
	v_rcp_f32_e32 v218, v218
	v_rcp_f32_e32 v219, v219
	v_pk_mul_f32 v[204:205], v[200:201], v[204:205]
	v_pk_mul_f32 v[200:201], v[208:209], v[216:217]
	v_lshlrev_b64 v[216:217], 14, v[160:161]
	v_pk_mul_f32 v[214:215], v[196:197], v[214:215]
	v_pk_mul_f32 v[196:197], v[206:207], v[218:219]
	v_lshl_add_u64 v[216:217], s[20:21], 0, v[216:217]
	v_cvt_pk_bf16_f32 v206, v214, v215
	v_cvt_pk_bf16_f32 v207, v204, v205
	v_cvt_pk_bf16_f32 v208, v200, v201
	v_cvt_pk_bf16_f32 v209, v196, v197
	v_lshl_add_u64 v[170:171], v[216:217], 0, v[170:171]
	global_store_dwordx4 v[170:171], v[206:209], off
	s_nop 1
	v_pk_mul_f32 v[206:207], v[210:211], v[210:211]
	s_nop 0
	v_pk_fma_f32 v[202:203], v[202:203], v[202:203], v[206:207]
	s_nop 0
	v_pk_fma_f32 v[202:203], v[212:213], v[212:213], v[202:203]
	v_pk_mul_f32 v[212:213], v[58:59], v[184:185]
	v_pk_fma_f32 v[208:209], v[214:215], v[214:215], v[202:203]
	v_pk_mul_f32 v[202:203], v[60:61], v[190:191]
	v_pk_mul_f32 v[214:215], v[56:57], v[182:183]
	v_mul_f32_e32 v206, 0xbdd2d3e7, v202
	v_fmaak_f32 v206, v202, v206, 0xc0135761
	v_mul_f32_e32 v206, v202, v206
	v_exp_f32_e32 v210, v206
	v_pk_mul_f32 v[206:207], v[62:63], v[186:187]
	v_mul_f32_e32 v211, 0xbdd2d3e7, v203
	v_fmaak_f32 v211, v203, v211, 0xc0135761
	v_mul_f32_e32 v216, 0xbdd2d3e7, v206
; DI float gelu_tanh(float x) { const float t = x * (1.5957691216f + 0.0713548163f * x * x); return x * __builtin_amdgcn_rcpf(1.f + __builtin_amdgcn_exp2f(-1.4426950409f * t)); }
; #define ROWS8 _Pragma("unroll") for (int ai = 0; ai < 2; ++ai) _Pragma("unroll") for (int m = 0; m < 4; ++m) if (ai == 0 || !hf)
; #define PK8(v0, v1) ({ const u32x2 h0_ = pk4(v0), h1_ = pk4(v1); (u32x4){h0_.x, h0_.y, h1_.x, h1_.y}; })
;     DI void operator()(const Acc& acc, const Unit& u, int wr, int wc, int fr, int fq) const {
;     ...
;                 for (int bj = 0; bj < 2; ++bj) { const int cc = colp + bj * HALF;
;                     f32x4 sq0 = {0.f, 0.f, 0.f, 0.f}, sq1 = {0.f, 0.f, 0.f, 0.f};
;                     ROWS8 { const int r = row0 + ai * HALF + m * 16; f32x4 v0 = acc[ai][bj][m][0] * rsc[bj][0], v1 = acc[ai][bj][m][1] * rsc[bj][1];
;                         v0[0] = gelu_tanh(v0[0]); v0[1] = gelu_tanh(v0[1]); v0[2] = gelu_tanh(v0[2]); v0[3] = gelu_tanh(v0[3]);
;                         v1[0] = gelu_tanh(v1[0]); v1[1] = gelu_tanh(v1[1]); v1[2] = gelu_tanh(v1[2]); v1[3] = gelu_tanh(v1[3]);
;                         sq0 += v0 * v0; sq1 += v1 * v1; *(u32x4*)(WSB(OFF_VT) + (size_t)r * 8192 + cc) = PK8(v0, v1); }
; #pragma unroll
;                     for (int j = 0; j < 8; ++j) { float t = j < 4 ? sq0[j & 3] : sq1[j & 3];
;                         t += __shfl_xor(t, 1); t += __shfl_xor(t, 2); t += __shfl_xor(t, 4); t += __shfl_xor(t, 8);
;                         if (fr == 0) unsafeAtomicAdd(ssqv + cc + j, t); }
	v_mul_f32_e32 v211, v203, v211
	v_fmaak_f32 v216, v206, v216, 0xc0135761
	v_mul_f32_e32 v216, v206, v216
	v_exp_f32_e32 v211, v211
	v_exp_f32_e32 v218, v216
	v_add_f32_e32 v210, 1.0, v210
	v_rcp_f32_e32 v216, v210
	v_add_f32_e32 v210, 1.0, v211
	v_rcp_f32_e32 v217, v210
	v_add_f32_e32 v210, 1.0, v218
	v_mul_f32_e32 v211, 0xbdd2d3e7, v207
	v_mul_f32_e32 v218, 0xbdd2d3e7, v214
	v_mul_f32_e32 v219, 0xbdd2d3e7, v215
	v_mul_f32_e32 v220, 0xbdd2d3e7, v212
	v_mul_f32_e32 v221, 0xbdd2d3e7, v213
	v_fmaak_f32 v211, v207, v211, 0xc0135761
	v_fmaak_f32 v218, v214, v218, 0xc0135761
	v_fmaak_f32 v219, v215, v219, 0xc0135761
	v_fmaak_f32 v220, v212, v220, 0xc0135761
	v_fmaak_f32 v221, v213, v221, 0xc0135761
	v_mul_f32_e32 v211, v207, v211
	v_mul_f32_e32 v218, v214, v218
	v_mul_f32_e32 v219, v215, v219
	v_mul_f32_e32 v220, v212, v220
	v_mul_f32_e32 v221, v213, v221
	v_exp_f32_e32 v211, v211
	v_exp_f32_e32 v218, v218
	v_exp_f32_e32 v219, v219
	v_exp_f32_e32 v220, v220
	v_exp_f32_e32 v221, v221
	v_add_f32_e32 v211, 1.0, v211
	v_add_f32_e32 v218, 1.0, v218
	v_add_f32_e32 v219, 1.0, v219
	v_add_f32_e32 v220, 1.0, v220
	v_add_f32_e32 v221, 1.0, v221
	v_rcp_f32_e32 v210, v210
	v_rcp_f32_e32 v211, v211
	v_rcp_f32_e32 v218, v218
	v_rcp_f32_e32 v220, v220
	v_rcp_f32_e32 v221, v221
	v_rcp_f32_e32 v219, v219
	v_pk_mul_f32 v[216:217], v[202:203], v[216:217]
	v_pk_mul_f32 v[210:211], v[206:207], v[210:211]
	v_pk_mul_f32 v[202:203], v[212:213], v[220:221]
	v_pk_mul_f32 v[206:207], v[214:215], v[218:219]
	v_pk_fma_f32 v[218:219], v[216:217], v[216:217], v[208:209]
	v_add_co_u32_e32 v208, vcc, s69, v138
	v_cvt_pk_bf16_f32 v212, v216, v217
	v_cvt_pk_bf16_f32 v213, v210, v211
	v_cvt_pk_bf16_f32 v214, v206, v207
	v_cvt_pk_bf16_f32 v215, v202, v203
	v_addc_co_u32_e32 v209, vcc, 0, v139, vcc
	global_store_dwordx4 v[208:209], v[212:215], off
	v_pk_mul_f32 v[208:209], v[44:45], v[190:191]
	v_pk_mul_f32 v[220:221], v[40:41], v[182:183]
	v_mul_f32_e32 v212, 0xbdd2d3e7, v208
	v_fmaak_f32 v212, v208, v212, 0xc0135761
	v_mul_f32_e32 v212, v208, v212
	v_exp_f32_e32 v216, v212
	v_pk_mul_f32 v[212:213], v[46:47], v[186:187]
	v_pk_mul_f32 v[214:215], v[42:43], v[184:185]
	v_mul_f32_e32 v234, 0xbdd2d3e7, v213
	v_fmaak_f32 v234, v213, v234, 0xc0135761
	v_mul_f32_e32 v222, 0xbdd2d3e7, v212
	v_mul_f32_e32 v234, v213, v234
	v_fmaak_f32 v222, v212, v222, 0xc0135761
	v_mul_f32_e32 v222, v212, v222
	v_exp_f32_e32 v235, v234
	v_mul_f32_e32 v234, 0xbdd2d3e7, v220
	v_fmaak_f32 v234, v220, v234, 0xc0135761
	v_exp_f32_e32 v222, v222
	v_mul_f32_e32 v234, v220, v234
	v_exp_f32_e32 v236, v234
	v_add_f32_e32 v222, 1.0, v222
	v_rcp_f32_e32 v234, v222
	v_add_f32_e32 v222, 1.0, v235
	v_rcp_f32_e32 v235, v222
	v_add_f32_e32 v222, 1.0, v236
	v_mul_f32_e32 v237, 0xbdd2d3e7, v214
	v_mul_f32_e32 v217, 0xbdd2d3e7, v209
	v_rcp_f32_e32 v236, v222
	v_mul_f32_e32 v222, 0xbdd2d3e7, v221
	v_fmaak_f32 v237, v214, v237, 0xc0135761
	v_mul_f32_e32 v238, 0xbdd2d3e7, v215
	v_fmaak_f32 v217, v209, v217, 0xc0135761
	v_fmaak_f32 v222, v221, v222, 0xc0135761
	v_mul_f32_e32 v237, v214, v237
	v_fmaak_f32 v238, v215, v238, 0xc0135761
	v_mul_f32_e32 v217, v209, v217
	v_mul_f32_e32 v222, v221, v222
	v_mul_f32_e32 v238, v215, v238
	v_exp_f32_e32 v237, v237
	v_exp_f32_e32 v217, v217
	v_exp_f32_e32 v222, v222
	v_exp_f32_e32 v239, v238
	v_add_f32_e32 v237, 1.0, v237
	v_add_f32_e32 v216, 1.0, v216
	v_add_f32_e32 v217, 1.0, v217
	v_add_f32_e32 v222, 1.0, v222
	v_rcp_f32_e32 v238, v237
	v_add_f32_e32 v237, 1.0, v239
	v_rcp_f32_e32 v216, v216
	v_rcp_f32_e32 v217, v217
	v_rcp_f32_e32 v239, v237
	v_rcp_f32_e32 v237, v222
	v_pk_mul_f32 v[240:241], v[208:209], v[216:217]
	v_pk_mul_f32 v[216:217], v[212:213], v[234:235]
	v_pk_mul_f32 v[208:209], v[214:215], v[238:239]
	v_pk_mul_f32 v[212:213], v[220:221], v[236:237]
	v_add_co_u32_e32 v214, vcc, s70, v138
	v_pk_fma_f32 v[234:235], v[240:241], v[240:241], v[218:219]
	v_cvt_pk_bf16_f32 v218, v240, v241
	v_cvt_pk_bf16_f32 v219, v216, v217
	v_cvt_pk_bf16_f32 v220, v212, v213
	v_cvt_pk_bf16_f32 v221, v208, v209
	v_addc_co_u32_e32 v215, vcc, 0, v139, vcc
	global_store_dwordx4 v[214:215], v[218:221], off
	v_pk_mul_f32 v[214:215], v[28:29], v[190:191]
	v_pk_mul_f32 v[238:239], v[24:25], v[182:183]
	v_mul_f32_e32 v218, 0xbdd2d3e7, v214
	v_fmaak_f32 v218, v214, v218, 0xc0135761
	v_mul_f32_e32 v218, v214, v218
	v_exp_f32_e32 v220, v218
	v_pk_mul_f32 v[218:219], v[30:31], v[186:187]
	v_mul_f32_e32 v221, 0xbdd2d3e7, v215
	v_fmaak_f32 v221, v215, v221, 0xc0135761
	v_mul_f32_e32 v222, 0xbdd2d3e7, v218
	v_mul_f32_e32 v221, v215, v221
	v_fmaak_f32 v222, v218, v222, 0xc0135761
; DI float gelu_tanh(float x) { const float t = x * (1.5957691216f + 0.0713548163f * x * x); return x * __builtin_amdgcn_rcpf(1.f + __builtin_amdgcn_exp2f(-1.4426950409f * t)); }
; #define ROWS8 _Pragma("unroll") for (int ai = 0; ai < 2; ++ai) _Pragma("unroll") for (int m = 0; m < 4; ++m) if (ai == 0 || !hf)
; #define PK8(v0, v1) ({ const u32x2 h0_ = pk4(v0), h1_ = pk4(v1); (u32x4){h0_.x, h0_.y, h1_.x, h1_.y}; })
;     DI void operator()(const Acc& acc, const Unit& u, int wr, int wc, int fr, int fq) const {
;     ...
;                 for (int bj = 0; bj < 2; ++bj) { const int cc = colp + bj * HALF;
;                     f32x4 sq0 = {0.f, 0.f, 0.f, 0.f}, sq1 = {0.f, 0.f, 0.f, 0.f};
;                     ROWS8 { const int r = row0 + ai * HALF + m * 16; f32x4 v0 = acc[ai][bj][m][0] * rsc[bj][0], v1 = acc[ai][bj][m][1] * rsc[bj][1];
;                         v0[0] = gelu_tanh(v0[0]); v0[1] = gelu_tanh(v0[1]); v0[2] = gelu_tanh(v0[2]); v0[3] = gelu_tanh(v0[3]);
;                         v1[0] = gelu_tanh(v1[0]); v1[1] = gelu_tanh(v1[1]); v1[2] = gelu_tanh(v1[2]); v1[3] = gelu_tanh(v1[3]);
;                         sq0 += v0 * v0; sq1 += v1 * v1; *(u32x4*)(WSB(OFF_VT) + (size_t)r * 8192 + cc) = PK8(v0, v1); }
; #pragma unroll
;                     for (int j = 0; j < 8; ++j) { float t = j < 4 ? sq0[j & 3] : sq1[j & 3];
;                         t += __shfl_xor(t, 1); t += __shfl_xor(t, 2); t += __shfl_xor(t, 4); t += __shfl_xor(t, 8);
;                         if (fr == 0) unsafeAtomicAdd(ssqv + cc + j, t); }
	v_mul_f32_e32 v222, v218, v222
	v_exp_f32_e32 v221, v221
	v_exp_f32_e32 v222, v222
	v_add_f32_e32 v220, 1.0, v220
	v_rcp_f32_e32 v240, v220
	v_add_f32_e32 v220, 1.0, v221
	v_rcp_f32_e32 v241, v220
	v_add_f32_e32 v220, 1.0, v222
	v_mul_f32_e32 v222, 0xbdd2d3e7, v238
	v_fmaak_f32 v222, v238, v222, 0xc0135761
	v_mul_f32_e32 v222, v238, v222
	v_exp_f32_e32 v222, v222
	v_pk_mul_f32 v[236:237], v[26:27], v[184:185]
	v_mul_f32_e32 v221, 0xbdd2d3e7, v219
	v_mul_f32_e32 v243, 0xbdd2d3e7, v236
	v_add_f32_e32 v222, 1.0, v222
	v_rcp_f32_e32 v242, v222
	v_mul_f32_e32 v222, 0xbdd2d3e7, v239
	v_fmaak_f32 v243, v236, v243, 0xc0135761
	v_mul_f32_e32 v244, 0xbdd2d3e7, v237
	v_fmaak_f32 v221, v219, v221, 0xc0135761
	v_fmaak_f32 v222, v239, v222, 0xc0135761
	v_mul_f32_e32 v243, v236, v243
	v_fmaak_f32 v244, v237, v244, 0xc0135761
	v_mul_f32_e32 v221, v219, v221
	v_mul_f32_e32 v222, v239, v222
	v_mul_f32_e32 v244, v237, v244
	v_exp_f32_e32 v243, v243
	v_exp_f32_e32 v221, v221
	v_exp_f32_e32 v222, v222
	v_exp_f32_e32 v245, v244
	v_add_f32_e32 v243, 1.0, v243
	v_add_f32_e32 v221, 1.0, v221
	v_add_f32_e32 v222, 1.0, v222
	v_rcp_f32_e32 v244, v243
	v_add_f32_e32 v243, 1.0, v245
	v_rcp_f32_e32 v220, v220
	v_rcp_f32_e32 v221, v221
	v_rcp_f32_e32 v245, v243
	v_rcp_f32_e32 v243, v222
	v_pk_mul_f32 v[240:241], v[214:215], v[240:241]
	v_pk_mul_f32 v[220:221], v[218:219], v[220:221]
	v_pk_mul_f32 v[214:215], v[236:237], v[244:245]
	v_pk_mul_f32 v[218:219], v[238:239], v[242:243]
	v_pk_fma_f32 v[238:239], v[240:241], v[240:241], v[234:235]
	v_cvt_pk_bf16_f32 v234, v240, v241
	v_add_co_u32_e32 v240, vcc, s71, v138
	v_pk_mul_f32 v[190:191], v[12:13], v[190:191]
	v_cvt_pk_bf16_f32 v235, v220, v221
	v_cvt_pk_bf16_f32 v236, v218, v219
	v_cvt_pk_bf16_f32 v237, v214, v215
	v_addc_co_u32_e32 v241, vcc, 0, v139, vcc
	v_mul_f32_e32 v222, 0xbdd2d3e7, v190
	global_store_dwordx4 v[240:241], v[234:237], off
	v_fmaak_f32 v222, v190, v222, 0xc0135761
	v_mul_f32_e32 v222, v190, v222
	v_mul_f32_e32 v234, 0xbdd2d3e7, v191
	v_fmaak_f32 v234, v191, v234, 0xc0135761
	v_mul_f32_e32 v234, v191, v234
	v_exp_f32_e32 v222, v222
	v_exp_f32_e32 v235, v234
	v_pk_mul_f32 v[186:187], v[14:15], v[186:187]
	v_add_f32_e32 v222, 1.0, v222
	v_rcp_f32_e32 v234, v222
	v_add_f32_e32 v222, 1.0, v235
	v_mul_f32_e32 v235, 0xbdd2d3e7, v186
	v_fmaak_f32 v235, v186, v235, 0xc0135761
	v_mul_f32_e32 v235, v186, v235
	v_exp_f32_e32 v236, v235
	v_mul_f32_e32 v235, 0xbdd2d3e7, v187
	v_fmaak_f32 v235, v187, v235, 0xc0135761
	v_mul_f32_e32 v235, v187, v235
	v_exp_f32_e32 v237, v235
	v_rcp_f32_e32 v235, v222
	v_pk_mul_f32 v[240:241], v[8:9], v[182:183]
	v_pk_mul_f32 v[184:185], v[10:11], v[184:185]
	v_mul_f32_e32 v182, 0xbdd2d3e7, v240
	v_pk_mul_f32 v[234:235], v[190:191], v[234:235]
	v_fmaak_f32 v182, v240, v182, 0xc0135761
	v_mul_f32_e32 v190, 0xbdd2d3e7, v184
	v_mul_f32_e32 v182, v240, v182
	v_fmaak_f32 v190, v184, v190, 0xc0135761
	v_add_f32_e32 v222, 1.0, v236
	v_mul_f32_e32 v190, v184, v190
	v_rcp_f32_e32 v236, v222
	v_add_f32_e32 v222, 1.0, v237
	v_exp_f32_e32 v182, v182
	v_rcp_f32_e32 v237, v222
	v_exp_f32_e32 v190, v190
	v_mul_f32_e32 v183, 0xbdd2d3e7, v241
	v_fmaak_f32 v183, v241, v183, 0xc0135761
	v_add_f32_e32 v182, 1.0, v182
	v_pk_mul_f32 v[186:187], v[186:187], v[236:237]
	v_mul_f32_e32 v183, v241, v183
	v_rcp_f32_e32 v236, v182
	v_add_f32_e32 v182, 1.0, v190
	v_pk_fma_f32 v[190:191], v[234:235], v[234:235], v[238:239]
	ds_bpermute_b32 v238, v226, v190
	v_exp_f32_e32 v183, v183
	v_rcp_f32_e32 v182, v182
	v_add_f32_e32 v222, 1.0, v183
	v_mul_f32_e32 v183, 0xbdd2d3e7, v185
	s_waitcnt lgkmcnt(0)
	v_add_f32_e32 v190, v190, v238
	v_fmaak_f32 v183, v185, v183, 0xc0135761
	v_rcp_f32_e32 v237, v222
	ds_bpermute_b32 v222, v227, v190
	v_mul_f32_e32 v183, v185, v183
	v_exp_f32_e32 v183, v183
	s_waitcnt lgkmcnt(0)
	v_add_f32_e32 v190, v190, v222
	ds_bpermute_b32 v222, v228, v190
	v_add_f32_e32 v183, 1.0, v183
	v_rcp_f32_e32 v183, v183
	s_waitcnt lgkmcnt(0)
	v_add_f32_e32 v190, v190, v222
	v_pk_mul_f32 v[182:183], v[184:185], v[182:183]
	v_pk_mul_f32 v[184:185], v[240:241], v[236:237]
	v_cvt_pk_bf16_f32 v236, v234, v235
	ds_bpermute_b32 v234, v229, v190
	v_add_co_u32_e32 v240, vcc, 0x2c0000, v138
	v_cvt_pk_bf16_f32 v237, v186, v187
	v_cvt_pk_bf16_f32 v238, v184, v185
	v_cvt_pk_bf16_f32 v239, v182, v183
	v_addc_co_u32_e32 v241, vcc, 0, v139, vcc
	global_store_dwordx4 v[240:241], v[236:239], off
	s_and_saveexec_b64 s[4:5], s[2:3]
	s_cbranch_execz .LBB0_331
	s_waitcnt lgkmcnt(0)
	v_add_f32_e32 v190, v190, v234
	global_atomic_add_f32 v[136:137], v190, off

; DI u32x2 pk4(f32x4 v) { u32x2 r; r.x = pk2(v[0], v[1]); r.y = pk2(v[2], v[3]); return r; }
; DI float silu_f(float x) { return x * __builtin_amdgcn_rcpf(1.f + __builtin_amdgcn_exp2f(-1.4426950409f * x)); }
; #define ROWS8 _Pragma("unroll") for (int ai = 0; ai < 2; ++ai) _Pragma("unroll") for (int m = 0; m < 4; ++m) if (ai == 0 || !hf)
; #define LOAD_ROW_RS(rsv, ssqp, invn) float rsv[2][4]; ROWS8_ALL rsv[ai][m] = (ssqp)[row0 + ai * HALF + m * 16]; ROWS8_ALL rsv[ai][m] = rstd_of(rsv[ai][m], invn)
; DI float rstd_of(float ssq, float inv_n) { return __builtin_amdgcn_rsqf(ssq * inv_n + 1e-6f); }
;     DI void operator()(const Acc& acc, const Unit& u, int wr, int wc, int fr, int fq) const {
;     ...
;             LOAD_ROW_RS(rsv, SSQ(PH == 5 ? 2 : 6), 1.f / 2048.f);
;             const int ac0 = u.pn * 128 + wc * 32 + 8 * fq;
;             ROWS8 { const int r = row0 + ai * HALF + m * 16; const float rs = rsv[ai][m];
;                 u32x4 w;
; #pragma unroll
;                 for (int bj = 0; bj < 2; ++bj) { const f32x4 g = acc[ai][bj][m][0] * rs, uu = acc[ai][bj][m][1] * rs;
;                     f32x4 a; a[0] = silu_f(g[0]) * uu[0]; a[1] = silu_f(g[1]) * uu[1]; a[2] = silu_f(g[2]) * uu[2]; a[3] = silu_f(g[3]) * uu[3];
;                     const u32x2 h = pk4(a); if (bj == 0) { w.x = h.x; w.y = h.y; } else { w.z = h.x; w.w = h.y; } }
;                 *(u32x4*)(WSB(OFF_ACT) + (size_t)r * DFF + ac0) = w;
.Lkrot_2_exit:
	s_barrier
.Lpeel_2_exit:
	s_mov_b32 s99, 0x40053526
	v_lshl_add_u32 v142, s22, 8, v155
	v_or_b32_e32 v156, 16, v142
	v_ashrrev_i32_e32 v157, 31, v156
	v_or_b32_e32 v152, 32, v142
	v_or_b32_e32 v150, 48, v142
	v_lshl_add_u64 v[138:139], v[156:157], 2, s[10:11]
	v_ashrrev_i32_e32 v153, 31, v152
	v_ashrrev_i32_e32 v151, 31, v150
	v_ashrrev_i32_e32 v143, 31, v142
	v_lshl_add_u64 v[140:141], v[152:153], 2, s[10:11]
	v_lshl_add_u64 v[144:145], v[150:151], 2, s[10:11]
	v_lshl_add_u64 v[146:147], v[142:143], 2, s[10:11]
	v_add_u32_e32 v148, 0x80, v142
	v_add_u32_e32 v146, 0x90, v142
	v_add_u32_e32 v144, 0xa0, v142
	v_add_u32_e32 v138, 0xb0, v142
	v_ashrrev_i32_e32 v149, 31, v148
	v_ashrrev_i32_e32 v147, 31, v146
	v_ashrrev_i32_e32 v145, 31, v144
	v_ashrrev_i32_e32 v139, 31, v138
	v_lshl_add_u64 v[140:141], v[148:149], 2, s[10:11]
	v_lshl_add_u64 v[164:165], v[146:147], 2, s[10:11]
	v_lshl_add_u64 v[166:167], v[144:145], 2, s[10:11]
	v_lshl_add_u64 v[168:169], v[138:139], 2, s[10:11]
	v_lshl_add_u32 v164, s56, 7, v159
	v_mov_b64_e32 v[140:141], s[12:13]
	v_ashrrev_i32_e32 v165, 31, v164
	v_mad_i64_i32 v[166:167], s[24:25], v142, s55, v[140:141]
	v_lshlrev_b64 v[142:143], 1, v[164:165]
	v_lshl_add_u64 v[164:165], v[166:167], 0, v[142:143]
	s_and_b64 vcc, exec, s[2:3]
	s_mov_b32 s56, s14
	s_mov_b32 s22, s16
	s_mov_b64 s[30:31], s[18:19]
	s_mov_b64 s[28:29], s[20:21]
	v_mov_b32_e32 v151, v221
	v_mov_b32_e32 v153, v222
	v_mov_b32_e32 v154, v223
	v_mov_b32_e32 v157, v220
	v_mov_b32_e32 v139, v224
	v_mov_b32_e32 v145, v225
	v_mov_b32_e32 v147, v226
	v_mov_b32_e32 v149, v227
	v_fmamk_f32 v151, v151, 0x3a000000, v163
	v_rsq_f32_e32 v168, v151
	s_nop 0
	v_mul_f32_e32 v168, 0xbfb8aa3b, v168
	v_fmamk_f32 v153, v153, 0x3a000000, v163
	v_fmamk_f32 v157, v157, 0x3a000000, v163
	v_rsq_f32_e32 v166, v157
	s_nop 0
	v_mul_f32_e32 v166, 0xbfb8aa3b, v166
	v_rsq_f32_e32 v170, v153
	s_nop 0
	v_mul_f32_e32 v170, 0xbfb8aa3b, v170
	v_pk_mul_f32 v[118:119], v[118:119], v[168:169] op_sel_hi:[1,0]
	v_pk_mul_f32 v[116:117], v[116:117], v[168:169] op_sel_hi:[1,0]
	v_pk_mul_f32 v[126:127], v[126:127], v[166:167] op_sel_hi:[1,0]
	v_pk_mul_f32 v[124:125], v[124:125], v[166:167] op_sel_hi:[1,0]
	v_pk_mul_f32 v[114:115], v[114:115], v[166:167] op_sel_hi:[1,0]
	v_pk_mul_f32 v[112:113], v[112:113], v[166:167] op_sel_hi:[1,0]
	v_pk_mul_f32 v[122:123], v[122:123], v[166:167] op_sel_hi:[1,0]
	v_pk_mul_f32 v[120:121], v[120:121], v[166:167] op_sel_hi:[1,0]
	v_pk_mul_f32 v[110:111], v[110:111], v[166:167] op_sel_hi:[1,0]
	v_pk_mul_f32 v[108:109], v[108:109], v[166:167] op_sel_hi:[1,0]
	v_exp_f32_e32 v151, v124
	v_exp_f32_e32 v153, v125
	v_exp_f32_e32 v157, v126
	v_exp_f32_e32 v166, v127
	v_exp_f32_e32 v167, v112
	v_exp_f32_e32 v169, v113
	v_exp_f32_e32 v171, v114
	v_exp_f32_e32 v172, v115
	v_exp_f32_e32 v178, v116
	v_fma_f32 v151, v151, s99, s99
	v_fma_f32 v153, v153, s99, s99
	v_fma_f32 v157, v157, s99, s99
	v_fma_f32 v173, v166, s99, s99
	v_fma_f32 v174, v167, s99, s99
	v_fma_f32 v169, v169, s99, s99
	v_fma_f32 v171, v171, s99, s99
	v_fma_f32 v177, v172, s99, s99
	v_rcp_f32_e32 v166, v151
	v_rcp_f32_e32 v167, v153
	v_rcp_f32_e32 v172, v157
	v_rcp_f32_e32 v173, v173
	v_rcp_f32_e32 v174, v174
	v_rcp_f32_e32 v175, v169
	v_rcp_f32_e32 v176, v171
	v_rcp_f32_e32 v177, v177
	v_pk_mul_f32 v[124:125], v[124:125], v[166:167]
	v_pk_mul_f32 v[126:127], v[126:127], v[172:173]
	v_pk_mul_f32 v[112:113], v[112:113], v[174:175]
	v_pk_mul_f32 v[114:115], v[114:115], v[176:177]
	v_pk_mul_f32 v[120:121], v[120:121], v[124:125]
	v_pk_mul_f32 v[122:123], v[122:123], v[126:127]
	v_pk_mul_f32 v[112:113], v[108:109], v[112:113]
	v_pk_mul_f32 v[114:115], v[110:111], v[114:115]
	v_cvt_pk_bf16_f32 v108, v120, v121
	v_cvt_pk_bf16_f32 v109, v122, v123
	v_cvt_pk_bf16_f32 v110, v112, v113
	v_cvt_pk_bf16_f32 v111, v114, v115
	global_store_dwordx4 v[164:165], v[108:111], off
	v_pk_mul_f32 v[104:105], v[104:105], v[168:169] op_sel_hi:[1,0]
	v_pk_mul_f32 v[106:107], v[106:107], v[168:169] op_sel_hi:[1,0]
	v_exp_f32_e32 v109, v117
	v_exp_f32_e32 v110, v118
	v_exp_f32_e32 v111, v119
	v_fma_f32 v108, v178, s99, s99
	v_fma_f32 v109, v109, s99, s99
	v_rcp_f32_e32 v108, v108
	v_rcp_f32_e32 v109, v109
	v_fma_f32 v110, v110, s99, s99
	v_fma_f32 v111, v111, s99, s99
	v_rcp_f32_e32 v110, v110
	v_rcp_f32_e32 v111, v111
	v_pk_mul_f32 v[108:109], v[116:117], v[108:109]
	v_pk_mul_f32 v[100:101], v[100:101], v[168:169] op_sel_hi:[1,0]
	v_pk_mul_f32 v[104:105], v[104:105], v[108:109]
	v_pk_mul_f32 v[108:109], v[118:119], v[110:111]
	v_cvt_pk_bf16_f32 v104, v104, v105
	v_pk_mul_f32 v[106:107], v[106:107], v[108:109]
	v_pk_mul_f32 v[102:103], v[102:103], v[168:169] op_sel_hi:[1,0]
	v_cvt_pk_bf16_f32 v105, v106, v107
	v_exp_f32_e32 v106, v100
	v_exp_f32_e32 v107, v101
	v_exp_f32_e32 v108, v102
	v_exp_f32_e32 v109, v103
	v_fma_f32 v106, v106, s99, s99
	v_fma_f32 v107, v107, s99, s99
	v_rcp_f32_e32 v106, v106
	v_rcp_f32_e32 v107, v107
	v_fma_f32 v108, v108, s99, s99
	v_fma_f32 v109, v109, s99, s99
	v_rcp_f32_e32 v108, v108
	v_rcp_f32_e32 v109, v109
	v_pk_mul_f32 v[92:93], v[92:93], v[168:169] op_sel_hi:[1,0]
	v_pk_mul_f32 v[100:101], v[100:101], v[106:107]
	v_pk_mul_f32 v[94:95], v[94:95], v[168:169] op_sel_hi:[1,0]
	v_pk_mul_f32 v[92:93], v[92:93], v[100:101]
	v_pk_mul_f32 v[100:101], v[102:103], v[108:109]
	v_cvt_pk_bf16_f32 v106, v92, v93
	v_pk_mul_f32 v[94:95], v[94:95], v[100:101]
	v_mad_i64_i32 v[92:93], s[24:25], v156, s55, v[140:141]
	v_cvt_pk_bf16_f32 v107, v94, v95
	v_lshl_add_u64 v[92:93], v[92:93], 0, v[142:143]
	global_store_dwordx4 v[92:93], v[104:107], off
	v_pk_mul_f32 v[92:93], v[98:99], v[170:171] op_sel_hi:[1,0]
; DI u32x2 pk4(f32x4 v) { u32x2 r; r.x = pk2(v[0], v[1]); r.y = pk2(v[2], v[3]); return r; }
; DI float silu_f(float x) { return x * __builtin_amdgcn_rcpf(1.f + __builtin_amdgcn_exp2f(-1.4426950409f * x)); }
; #define ROWS8 _Pragma("unroll") for (int ai = 0; ai < 2; ++ai) _Pragma("unroll") for (int m = 0; m < 4; ++m) if (ai == 0 || !hf)
;     DI void operator()(const Acc& acc, const Unit& u, int wr, int wc, int fr, int fq) const {
;     ...
;             ROWS8 { const int r = row0 + ai * HALF + m * 16; const float rs = rsv[ai][m];
;                 u32x4 w;
; #pragma unroll
;                 for (int bj = 0; bj < 2; ++bj) { const f32x4 g = acc[ai][bj][m][0] * rs, uu = acc[ai][bj][m][1] * rs;
;                     f32x4 a; a[0] = silu_f(g[0]) * uu[0]; a[1] = silu_f(g[1]) * uu[1]; a[2] = silu_f(g[2]) * uu[2]; a[3] = silu_f(g[3]) * uu[3];
;                     const u32x2 h = pk4(a); if (bj == 0) { w.x = h.x; w.y = h.y; } else { w.z = h.x; w.w = h.y; } }
;                 *(u32x4*)(WSB(OFF_ACT) + (size_t)r * DFF + ac0) = w;
	v_pk_mul_f32 v[94:95], v[96:97], v[170:171] op_sel_hi:[1,0]
	v_exp_f32_e32 v96, v94
	v_exp_f32_e32 v97, v95
	v_exp_f32_e32 v98, v92
	v_exp_f32_e32 v99, v93
	v_fma_f32 v96, v96, s99, s99
	v_fma_f32 v97, v97, s99, s99
	v_fma_f32 v98, v98, s99, s99
	v_fma_f32 v99, v99, s99, s99
	v_rcp_f32_e32 v96, v96
	v_rcp_f32_e32 v97, v97
	v_rcp_f32_e32 v98, v98
	v_rcp_f32_e32 v99, v99
	v_pk_mul_f32 v[90:91], v[90:91], v[170:171] op_sel_hi:[1,0]
	v_pk_mul_f32 v[88:89], v[88:89], v[170:171] op_sel_hi:[1,0]
	v_pk_mul_f32 v[94:95], v[94:95], v[96:97]
	v_pk_mul_f32 v[92:93], v[92:93], v[98:99]
	v_pk_mul_f32 v[88:89], v[88:89], v[94:95]
	v_pk_mul_f32 v[90:91], v[90:91], v[92:93]
	v_pk_mul_f32 v[84:85], v[84:85], v[170:171] op_sel_hi:[1,0]
	v_cvt_pk_bf16_f32 v88, v88, v89
	v_cvt_pk_bf16_f32 v89, v90, v91
	v_pk_mul_f32 v[86:87], v[86:87], v[170:171] op_sel_hi:[1,0]
	v_exp_f32_e32 v90, v84
	v_exp_f32_e32 v91, v85
	v_exp_f32_e32 v92, v86
	v_exp_f32_e32 v93, v87
	v_fma_f32 v90, v90, s99, s99
	v_fma_f32 v91, v91, s99, s99
	v_rcp_f32_e32 v90, v90
	v_rcp_f32_e32 v91, v91
	v_fma_f32 v92, v92, s99, s99
	v_fma_f32 v93, v93, s99, s99
	v_rcp_f32_e32 v92, v92
	v_rcp_f32_e32 v93, v93
	v_fmamk_f32 v154, v154, 0x3a000000, v163
	v_rsq_f32_e32 v154, v154
	s_nop 0
	v_mul_f32_e32 v154, 0xbfb8aa3b, v154
	v_pk_mul_f32 v[76:77], v[76:77], v[170:171] op_sel_hi:[1,0]
	v_pk_mul_f32 v[84:85], v[84:85], v[90:91]
	v_pk_mul_f32 v[78:79], v[78:79], v[170:171] op_sel_hi:[1,0]
	v_pk_mul_f32 v[76:77], v[76:77], v[84:85]
	v_pk_mul_f32 v[84:85], v[86:87], v[92:93]
	v_cvt_pk_bf16_f32 v90, v76, v77
	v_pk_mul_f32 v[78:79], v[78:79], v[84:85]
	v_mad_i64_i32 v[76:77], s[24:25], v152, s55, v[140:141]
	v_cvt_pk_bf16_f32 v91, v78, v79
	v_lshl_add_u64 v[76:77], v[76:77], 0, v[142:143]
	global_store_dwordx4 v[76:77], v[88:91], off
	v_pk_mul_f32 v[76:77], v[82:83], v[154:155] op_sel_hi:[1,0]
	v_pk_mul_f32 v[78:79], v[80:81], v[154:155] op_sel_hi:[1,0]
	v_exp_f32_e32 v80, v78
	v_exp_f32_e32 v81, v79
	v_exp_f32_e32 v82, v76
	v_exp_f32_e32 v83, v77
	v_fma_f32 v80, v80, s99, s99
	v_fma_f32 v81, v81, s99, s99
	v_fma_f32 v82, v82, s99, s99
	v_fma_f32 v83, v83, s99, s99
	v_rcp_f32_e32 v80, v80
	v_rcp_f32_e32 v81, v81
	v_rcp_f32_e32 v82, v82
	v_rcp_f32_e32 v83, v83
	v_pk_mul_f32 v[74:75], v[74:75], v[154:155] op_sel_hi:[1,0]
	v_pk_mul_f32 v[72:73], v[72:73], v[154:155] op_sel_hi:[1,0]
	v_pk_mul_f32 v[78:79], v[78:79], v[80:81]
	v_pk_mul_f32 v[76:77], v[76:77], v[82:83]
	v_pk_mul_f32 v[72:73], v[72:73], v[78:79]
	v_pk_mul_f32 v[74:75], v[74:75], v[76:77]
	v_pk_mul_f32 v[68:69], v[68:69], v[154:155] op_sel_hi:[1,0]
	v_cvt_pk_bf16_f32 v72, v72, v73
	v_cvt_pk_bf16_f32 v73, v74, v75
	v_pk_mul_f32 v[70:71], v[70:71], v[154:155] op_sel_hi:[1,0]
	v_exp_f32_e32 v74, v68
	v_exp_f32_e32 v75, v69
	v_exp_f32_e32 v76, v70
	v_exp_f32_e32 v77, v71
	v_fma_f32 v74, v74, s99, s99
	v_fma_f32 v75, v75, s99, s99
	v_rcp_f32_e32 v74, v74
	v_rcp_f32_e32 v75, v75
	v_fma_f32 v76, v76, s99, s99
	v_fma_f32 v77, v77, s99, s99
	v_rcp_f32_e32 v76, v76
	v_rcp_f32_e32 v77, v77
	v_pk_mul_f32 v[64:65], v[64:65], v[154:155] op_sel_hi:[1,0]
	v_pk_mul_f32 v[68:69], v[68:69], v[74:75]
	v_pk_mul_f32 v[66:67], v[66:67], v[154:155] op_sel_hi:[1,0]
	v_pk_mul_f32 v[64:65], v[64:65], v[68:69]
	v_pk_mul_f32 v[68:69], v[70:71], v[76:77]
	v_cvt_pk_bf16_f32 v74, v64, v65
	v_pk_mul_f32 v[66:67], v[66:67], v[68:69]
	v_mad_i64_i32 v[64:65], s[24:25], v150, s55, v[140:141]
	v_cvt_pk_bf16_f32 v75, v66, v67
	v_fmamk_f32 v66, v139, 0x3a000000, v163
	v_rsq_f32_e32 v68, v66
	s_nop 0
	v_mul_f32_e32 v68, 0xbfb8aa3b, v68
	v_lshl_add_u64 v[64:65], v[64:65], 0, v[142:143]
	global_store_dwordx4 v[64:65], v[72:75], off
	v_fmamk_f32 v65, v147, 0x3a000000, v163
	v_rsq_f32_e32 v66, v65
	s_nop 0
	v_mul_f32_e32 v66, 0xbfb8aa3b, v66
	v_fmamk_f32 v65, v145, 0x3a000000, v163
	v_pk_mul_f32 v[60:61], v[60:61], v[68:69] op_sel_hi:[1,0]
	v_rsq_f32_e32 v70, v65
	s_nop 0
	v_mul_f32_e32 v70, 0xbfb8aa3b, v70
	v_exp_f32_e32 v65, v60
	v_exp_f32_e32 v67, v61
	v_pk_mul_f32 v[62:63], v[62:63], v[68:69] op_sel_hi:[1,0]
	v_fma_f32 v65, v65, s99, s99
	v_rcp_f32_e32 v72, v65
	v_fma_f32 v65, v67, s99, s99
	v_pk_mul_f32 v[58:59], v[58:59], v[68:69] op_sel_hi:[1,0]
	v_exp_f32_e32 v67, v62
	v_exp_f32_e32 v69, v63
	v_rcp_f32_e32 v73, v65
	v_fma_f32 v65, v67, s99, s99
	v_rcp_f32_e32 v74, v65
	v_fma_f32 v65, v69, s99, s99
	v_rcp_f32_e32 v75, v65
	v_pk_mul_f32 v[56:57], v[56:57], v[68:69] op_sel_hi:[1,0]
	v_pk_mul_f32 v[60:61], v[60:61], v[72:73]
	v_pk_mul_f32 v[52:53], v[52:53], v[68:69] op_sel_hi:[1,0]
	v_pk_mul_f32 v[56:57], v[56:57], v[60:61]
	v_pk_mul_f32 v[60:61], v[62:63], v[74:75]
	v_cvt_pk_bf16_f32 v56, v56, v57
	v_pk_mul_f32 v[58:59], v[58:59], v[60:61]
	v_pk_mul_f32 v[54:55], v[54:55], v[68:69] op_sel_hi:[1,0]
	v_cvt_pk_bf16_f32 v57, v58, v59
	v_exp_f32_e32 v58, v52
	v_exp_f32_e32 v59, v53
	v_exp_f32_e32 v60, v54
	v_exp_f32_e32 v61, v55
	v_fma_f32 v58, v58, s99, s99
	v_fma_f32 v59, v59, s99, s99
	v_rcp_f32_e32 v58, v58
	v_rcp_f32_e32 v59, v59
	v_fma_f32 v60, v60, s99, s99
	v_fma_f32 v61, v61, s99, s99
	v_rcp_f32_e32 v60, v60
	v_rcp_f32_e32 v61, v61
	v_pk_mul_f32 v[44:45], v[44:45], v[68:69] op_sel_hi:[1,0]
	v_pk_mul_f32 v[52:53], v[52:53], v[58:59]
	v_pk_mul_f32 v[46:47], v[46:47], v[68:69] op_sel_hi:[1,0]
	v_pk_mul_f32 v[44:45], v[44:45], v[52:53]
	v_pk_mul_f32 v[52:53], v[54:55], v[60:61]
	v_cvt_pk_bf16_f32 v58, v44, v45
	v_pk_mul_f32 v[46:47], v[46:47], v[52:53]
	v_mad_i64_i32 v[44:45], s[24:25], v148, s55, v[140:141]
; DI u32x2 pk4(f32x4 v) { u32x2 r; r.x = pk2(v[0], v[1]); r.y = pk2(v[2], v[3]); return r; }
; DI float silu_f(float x) { return x * __builtin_amdgcn_rcpf(1.f + __builtin_amdgcn_exp2f(-1.4426950409f * x)); }
; #define ROWS8 _Pragma("unroll") for (int ai = 0; ai < 2; ++ai) _Pragma("unroll") for (int m = 0; m < 4; ++m) if (ai == 0 || !hf)
;     DI void operator()(const Acc& acc, const Unit& u, int wr, int wc, int fr, int fq) const {
;     ...
;             ROWS8 { const int r = row0 + ai * HALF + m * 16; const float rs = rsv[ai][m];
;                 u32x4 w;
; #pragma unroll
;                 for (int bj = 0; bj < 2; ++bj) { const f32x4 g = acc[ai][bj][m][0] * rs, uu = acc[ai][bj][m][1] * rs;
;                     f32x4 a; a[0] = silu_f(g[0]) * uu[0]; a[1] = silu_f(g[1]) * uu[1]; a[2] = silu_f(g[2]) * uu[2]; a[3] = silu_f(g[3]) * uu[3];
;                     const u32x2 h = pk4(a); if (bj == 0) { w.x = h.x; w.y = h.y; } else { w.z = h.x; w.w = h.y; } }
;                 *(u32x4*)(WSB(OFF_ACT) + (size_t)r * DFF + ac0) = w;
	v_cvt_pk_bf16_f32 v59, v46, v47
	v_lshl_add_u64 v[44:45], v[44:45], 0, v[142:143]
	global_store_dwordx4 v[44:45], v[56:59], off
	v_pk_mul_f32 v[44:45], v[50:51], v[70:71] op_sel_hi:[1,0]
	v_pk_mul_f32 v[46:47], v[48:49], v[70:71] op_sel_hi:[1,0]
	v_exp_f32_e32 v48, v46
	v_exp_f32_e32 v49, v47
	v_exp_f32_e32 v50, v44
	v_exp_f32_e32 v51, v45
	v_fma_f32 v48, v48, s99, s99
	v_fma_f32 v49, v49, s99, s99
	v_fma_f32 v50, v50, s99, s99
	v_fma_f32 v51, v51, s99, s99
	v_rcp_f32_e32 v48, v48
	v_rcp_f32_e32 v49, v49
	v_rcp_f32_e32 v50, v50
	v_rcp_f32_e32 v51, v51
	v_pk_mul_f32 v[42:43], v[42:43], v[70:71] op_sel_hi:[1,0]
	v_pk_mul_f32 v[40:41], v[40:41], v[70:71] op_sel_hi:[1,0]
	v_pk_mul_f32 v[46:47], v[46:47], v[48:49]
	v_pk_mul_f32 v[44:45], v[44:45], v[50:51]
	v_pk_mul_f32 v[40:41], v[40:41], v[46:47]
	v_pk_mul_f32 v[42:43], v[42:43], v[44:45]
	v_pk_mul_f32 v[36:37], v[36:37], v[70:71] op_sel_hi:[1,0]
	v_cvt_pk_bf16_f32 v40, v40, v41
	v_cvt_pk_bf16_f32 v41, v42, v43
	v_pk_mul_f32 v[38:39], v[38:39], v[70:71] op_sel_hi:[1,0]
	v_exp_f32_e32 v42, v36
	v_exp_f32_e32 v43, v37
	v_exp_f32_e32 v44, v38
	v_exp_f32_e32 v45, v39
	v_fma_f32 v42, v42, s99, s99
	v_fma_f32 v43, v43, s99, s99
	v_rcp_f32_e32 v42, v42
	v_rcp_f32_e32 v43, v43
	v_fma_f32 v44, v44, s99, s99
	v_fma_f32 v45, v45, s99, s99
	v_rcp_f32_e32 v44, v44
	v_rcp_f32_e32 v45, v45
	v_pk_mul_f32 v[28:29], v[28:29], v[70:71] op_sel_hi:[1,0]
	v_pk_mul_f32 v[36:37], v[36:37], v[42:43]
	v_pk_mul_f32 v[30:31], v[30:31], v[70:71] op_sel_hi:[1,0]
	v_pk_mul_f32 v[28:29], v[28:29], v[36:37]
	v_pk_mul_f32 v[36:37], v[38:39], v[44:45]
	v_cvt_pk_bf16_f32 v42, v28, v29
	v_pk_mul_f32 v[30:31], v[30:31], v[36:37]
	v_mad_i64_i32 v[28:29], s[24:25], v146, s55, v[140:141]
	v_cvt_pk_bf16_f32 v43, v30, v31
	v_lshl_add_u64 v[28:29], v[28:29], 0, v[142:143]
	global_store_dwordx4 v[28:29], v[40:43], off
	v_pk_mul_f32 v[28:29], v[34:35], v[66:67] op_sel_hi:[1,0]
	v_pk_mul_f32 v[30:31], v[32:33], v[66:67] op_sel_hi:[1,0]
	v_exp_f32_e32 v32, v30
	v_exp_f32_e32 v33, v31
	v_exp_f32_e32 v34, v28
	v_exp_f32_e32 v35, v29
	v_fma_f32 v32, v32, s99, s99
	v_fma_f32 v33, v33, s99, s99
	v_fma_f32 v34, v34, s99, s99
	v_fma_f32 v35, v35, s99, s99
	v_rcp_f32_e32 v32, v32
	v_rcp_f32_e32 v33, v33
	v_rcp_f32_e32 v34, v34
	v_rcp_f32_e32 v35, v35
	v_pk_mul_f32 v[26:27], v[26:27], v[66:67] op_sel_hi:[1,0]
	v_pk_mul_f32 v[24:25], v[24:25], v[66:67] op_sel_hi:[1,0]
	v_pk_mul_f32 v[30:31], v[30:31], v[32:33]
	v_pk_mul_f32 v[28:29], v[28:29], v[34:35]
	v_pk_mul_f32 v[24:25], v[24:25], v[30:31]
	v_pk_mul_f32 v[26:27], v[26:27], v[28:29]
	v_pk_mul_f32 v[20:21], v[20:21], v[66:67] op_sel_hi:[1,0]
	v_cvt_pk_bf16_f32 v24, v24, v25
	v_cvt_pk_bf16_f32 v25, v26, v27
	v_pk_mul_f32 v[22:23], v[22:23], v[66:67] op_sel_hi:[1,0]
	v_exp_f32_e32 v26, v20
	v_exp_f32_e32 v27, v21
	v_exp_f32_e32 v28, v22
	v_exp_f32_e32 v29, v23
	v_fma_f32 v26, v26, s99, s99
	v_fma_f32 v27, v27, s99, s99
	v_rcp_f32_e32 v26, v26
	v_rcp_f32_e32 v27, v27
	v_fma_f32 v28, v28, s99, s99
	v_fma_f32 v29, v29, s99, s99
	v_rcp_f32_e32 v28, v28
	v_rcp_f32_e32 v29, v29
	v_fmamk_f32 v64, v149, 0x3a000000, v163
	v_rsq_f32_e32 v64, v64
	s_nop 0
	v_mul_f32_e32 v64, 0xbfb8aa3b, v64
	v_pk_mul_f32 v[12:13], v[12:13], v[66:67] op_sel_hi:[1,0]
	v_pk_mul_f32 v[20:21], v[20:21], v[26:27]
	v_pk_mul_f32 v[14:15], v[14:15], v[66:67] op_sel_hi:[1,0]
	v_pk_mul_f32 v[12:13], v[12:13], v[20:21]
	v_pk_mul_f32 v[20:21], v[22:23], v[28:29]
	v_cvt_pk_bf16_f32 v26, v12, v13
	v_pk_mul_f32 v[14:15], v[14:15], v[20:21]
	v_mad_i64_i32 v[12:13], s[24:25], v144, s55, v[140:141]
	v_cvt_pk_bf16_f32 v27, v14, v15
	v_lshl_add_u64 v[12:13], v[12:13], 0, v[142:143]
	global_store_dwordx4 v[12:13], v[24:27], off
	v_pk_mul_f32 v[12:13], v[18:19], v[64:65] op_sel_hi:[1,0]
	v_pk_mul_f32 v[14:15], v[16:17], v[64:65] op_sel_hi:[1,0]
	v_exp_f32_e32 v16, v14
	v_exp_f32_e32 v17, v15
	v_exp_f32_e32 v18, v12
	v_exp_f32_e32 v19, v13
	v_fma_f32 v16, v16, s99, s99
	v_fma_f32 v17, v17, s99, s99
	v_fma_f32 v18, v18, s99, s99
	v_fma_f32 v19, v19, s99, s99
	v_rcp_f32_e32 v16, v16
	v_rcp_f32_e32 v17, v17
	v_rcp_f32_e32 v18, v18
	v_rcp_f32_e32 v19, v19
	v_pk_mul_f32 v[10:11], v[10:11], v[64:65] op_sel_hi:[1,0]
	v_pk_mul_f32 v[8:9], v[8:9], v[64:65] op_sel_hi:[1,0]
	v_pk_mul_f32 v[14:15], v[14:15], v[16:17]
	v_pk_mul_f32 v[12:13], v[12:13], v[18:19]
	v_pk_mul_f32 v[8:9], v[8:9], v[14:15]
	v_pk_mul_f32 v[10:11], v[10:11], v[12:13]
	v_pk_mul_f32 v[4:5], v[4:5], v[64:65] op_sel_hi:[1,0]
	v_cvt_pk_bf16_f32 v8, v8, v9
	v_cvt_pk_bf16_f32 v9, v10, v11
	v_pk_mul_f32 v[6:7], v[6:7], v[64:65] op_sel_hi:[1,0]
	v_exp_f32_e32 v10, v4
	v_exp_f32_e32 v11, v5
	v_exp_f32_e32 v12, v6
	v_exp_f32_e32 v13, v7
	v_fma_f32 v10, v10, s99, s99
	v_fma_f32 v11, v11, s99, s99
	v_rcp_f32_e32 v10, v10
	v_rcp_f32_e32 v11, v11
	v_fma_f32 v12, v12, s99, s99
	v_fma_f32 v13, v13, s99, s99
	v_rcp_f32_e32 v12, v12
	v_rcp_f32_e32 v13, v13
	v_pk_mul_f32 v[0:1], v[0:1], v[64:65] op_sel_hi:[1,0]
	v_pk_mul_f32 v[4:5], v[4:5], v[10:11]
	v_pk_mul_f32 v[2:3], v[2:3], v[64:65] op_sel_hi:[1,0]
	v_pk_mul_f32 v[0:1], v[0:1], v[4:5]
	v_pk_mul_f32 v[4:5], v[6:7], v[12:13]
	v_cvt_pk_bf16_f32 v10, v0, v1
	v_pk_mul_f32 v[2:3], v[2:3], v[4:5]
	v_mad_i64_i32 v[0:1], s[24:25], v138, s55, v[140:141]
	v_cvt_pk_bf16_f32 v11, v2, v3
	v_lshl_add_u64 v[0:1], v[0:1], 0, v[142:143]
	global_store_dwordx4 v[0:1], v[8:11], off
	s_cbranch_vccz .LBB0_702
	s_waitcnt vmcnt(0)
	s_cmpk_gt_u32 s88, 0xff
	s_cbranch_scc1 .LBB0_709
	s_barrier

; DI u32x2 pk4(f32x4 v) { u32x2 r; r.x = pk2(v[0], v[1]); r.y = pk2(v[2], v[3]); return r; }
; DI float silu_f(float x) { return x * __builtin_amdgcn_rcpf(1.f + __builtin_amdgcn_exp2f(-1.4426950409f * x)); }
; #define ROWS8 _Pragma("unroll") for (int ai = 0; ai < 2; ++ai) _Pragma("unroll") for (int m = 0; m < 4; ++m) if (ai == 0 || !hf)
; #define LOAD_ROW_RS(rsv, ssqp, invn) float rsv[2][4]; ROWS8_ALL rsv[ai][m] = (ssqp)[row0 + ai * HALF + m * 16]; ROWS8_ALL rsv[ai][m] = rstd_of(rsv[ai][m], invn)
; DI float rstd_of(float ssq, float inv_n) { return __builtin_amdgcn_rsqf(ssq * inv_n + 1e-6f); }
;     DI void operator()(const Acc& acc, const Unit& u, int wr, int wc, int fr, int fq) const {
;     ...
;             LOAD_ROW_RS(rsv, SSQ(PH == 5 ? 2 : 6), 1.f / 2048.f);
;             const int ac0 = u.pn * 128 + wc * 32 + 8 * fq;
;             ROWS8 { const int r = row0 + ai * HALF + m * 16; const float rs = rsv[ai][m];
;                 u32x4 w;
; #pragma unroll
;                 for (int bj = 0; bj < 2; ++bj) { const f32x4 g = acc[ai][bj][m][0] * rs, uu = acc[ai][bj][m][1] * rs;
;                     f32x4 a; a[0] = silu_f(g[0]) * uu[0]; a[1] = silu_f(g[1]) * uu[1]; a[2] = silu_f(g[2]) * uu[2]; a[3] = silu_f(g[3]) * uu[3];
;                     const u32x2 h = pk4(a); if (bj == 0) { w.x = h.x; w.y = h.y; } else { w.z = h.x; w.w = h.y; } }
;                 *(u32x4*)(WSB(OFF_ACT) + (size_t)r * DFF + ac0) = w;
.Lkrot_7_exit:
	s_barrier
.Lpeel_7_exit:
	s_mov_b32 s99, 0x40053526
	v_lshl_add_u32 v142, s22, 8, v155
	v_or_b32_e32 v156, 16, v142
	v_ashrrev_i32_e32 v157, 31, v156
	v_or_b32_e32 v152, 32, v142
	v_or_b32_e32 v150, 48, v142
	v_lshl_add_u64 v[138:139], v[156:157], 2, s[10:11]
	v_ashrrev_i32_e32 v153, 31, v152
	v_ashrrev_i32_e32 v151, 31, v150
	v_ashrrev_i32_e32 v143, 31, v142
	v_lshl_add_u64 v[140:141], v[152:153], 2, s[10:11]
	v_lshl_add_u64 v[144:145], v[150:151], 2, s[10:11]
	v_lshl_add_u64 v[146:147], v[142:143], 2, s[10:11]
	v_add_u32_e32 v148, 0x80, v142
	v_add_u32_e32 v146, 0x90, v142
	v_add_u32_e32 v144, 0xa0, v142
	v_add_u32_e32 v138, 0xb0, v142
	v_ashrrev_i32_e32 v149, 31, v148
	v_ashrrev_i32_e32 v147, 31, v146
	v_ashrrev_i32_e32 v145, 31, v144
	v_ashrrev_i32_e32 v139, 31, v138
	v_lshl_add_u64 v[140:141], v[148:149], 2, s[10:11]
	v_lshl_add_u64 v[164:165], v[146:147], 2, s[10:11]
	v_lshl_add_u64 v[166:167], v[144:145], 2, s[10:11]
	v_lshl_add_u64 v[168:169], v[138:139], 2, s[10:11]
	v_lshl_add_u32 v164, s56, 7, v159
	v_mov_b64_e32 v[140:141], s[12:13]
	v_ashrrev_i32_e32 v165, 31, v164
	v_mad_i64_i32 v[166:167], s[24:25], v142, s55, v[140:141]
	v_lshlrev_b64 v[142:143], 1, v[164:165]
	v_lshl_add_u64 v[164:165], v[166:167], 0, v[142:143]
	s_and_b64 vcc, exec, s[2:3]
	s_mov_b32 s56, s14
	s_mov_b32 s22, s16
	s_mov_b64 s[30:31], s[18:19]
	s_mov_b64 s[28:29], s[20:21]
	v_mov_b32_e32 v151, v221
	v_mov_b32_e32 v153, v222
	v_mov_b32_e32 v154, v223
	v_mov_b32_e32 v157, v220
	v_mov_b32_e32 v139, v224
	v_mov_b32_e32 v145, v225
	v_mov_b32_e32 v147, v226
	v_mov_b32_e32 v149, v227
	v_fmamk_f32 v151, v151, 0x3a000000, v163
	v_rsq_f32_e32 v168, v151
	s_nop 0
	v_mul_f32_e32 v168, 0xbfb8aa3b, v168
	v_fmamk_f32 v153, v153, 0x3a000000, v163
	v_fmamk_f32 v157, v157, 0x3a000000, v163
	v_rsq_f32_e32 v166, v157
	s_nop 0
	v_mul_f32_e32 v166, 0xbfb8aa3b, v166
	v_rsq_f32_e32 v170, v153
	s_nop 0
	v_mul_f32_e32 v170, 0xbfb8aa3b, v170
	v_pk_mul_f32 v[118:119], v[118:119], v[168:169] op_sel_hi:[1,0]
	v_pk_mul_f32 v[116:117], v[116:117], v[168:169] op_sel_hi:[1,0]
	v_pk_mul_f32 v[126:127], v[126:127], v[166:167] op_sel_hi:[1,0]
	v_pk_mul_f32 v[124:125], v[124:125], v[166:167] op_sel_hi:[1,0]
	v_pk_mul_f32 v[114:115], v[114:115], v[166:167] op_sel_hi:[1,0]
	v_pk_mul_f32 v[112:113], v[112:113], v[166:167] op_sel_hi:[1,0]
	v_pk_mul_f32 v[122:123], v[122:123], v[166:167] op_sel_hi:[1,0]
	v_pk_mul_f32 v[120:121], v[120:121], v[166:167] op_sel_hi:[1,0]
	v_pk_mul_f32 v[110:111], v[110:111], v[166:167] op_sel_hi:[1,0]
	v_pk_mul_f32 v[108:109], v[108:109], v[166:167] op_sel_hi:[1,0]
	v_exp_f32_e32 v151, v124
	v_exp_f32_e32 v153, v125
	v_exp_f32_e32 v157, v126
	v_exp_f32_e32 v166, v127
	v_exp_f32_e32 v167, v112
	v_exp_f32_e32 v169, v113
	v_exp_f32_e32 v171, v114
	v_exp_f32_e32 v172, v115
	v_exp_f32_e32 v178, v116
	v_fma_f32 v151, v151, s99, s99
	v_fma_f32 v153, v153, s99, s99
	v_fma_f32 v157, v157, s99, s99
	v_fma_f32 v173, v166, s99, s99
	v_fma_f32 v174, v167, s99, s99
	v_fma_f32 v169, v169, s99, s99
	v_fma_f32 v171, v171, s99, s99
	v_fma_f32 v177, v172, s99, s99
	v_rcp_f32_e32 v166, v151
	v_rcp_f32_e32 v167, v153
	v_rcp_f32_e32 v172, v157
	v_rcp_f32_e32 v173, v173
	v_rcp_f32_e32 v174, v174
	v_rcp_f32_e32 v175, v169
	v_rcp_f32_e32 v176, v171
	v_rcp_f32_e32 v177, v177
	v_pk_mul_f32 v[124:125], v[124:125], v[166:167]
	v_pk_mul_f32 v[126:127], v[126:127], v[172:173]
	v_pk_mul_f32 v[112:113], v[112:113], v[174:175]
	v_pk_mul_f32 v[114:115], v[114:115], v[176:177]
	v_pk_mul_f32 v[120:121], v[120:121], v[124:125]
	v_pk_mul_f32 v[122:123], v[122:123], v[126:127]
	v_pk_mul_f32 v[112:113], v[108:109], v[112:113]
	v_pk_mul_f32 v[114:115], v[110:111], v[114:115]
	v_cvt_pk_bf16_f32 v108, v120, v121
	v_cvt_pk_bf16_f32 v109, v122, v123
	v_cvt_pk_bf16_f32 v110, v112, v113
	v_cvt_pk_bf16_f32 v111, v114, v115
	global_store_dwordx4 v[164:165], v[108:111], off
	v_pk_mul_f32 v[104:105], v[104:105], v[168:169] op_sel_hi:[1,0]
	v_pk_mul_f32 v[106:107], v[106:107], v[168:169] op_sel_hi:[1,0]
	v_exp_f32_e32 v109, v117
	v_exp_f32_e32 v110, v118
	v_exp_f32_e32 v111, v119
	v_fma_f32 v108, v178, s99, s99
	v_fma_f32 v109, v109, s99, s99
	v_rcp_f32_e32 v108, v108
	v_rcp_f32_e32 v109, v109
	v_fma_f32 v110, v110, s99, s99
	v_fma_f32 v111, v111, s99, s99
	v_rcp_f32_e32 v110, v110
	v_rcp_f32_e32 v111, v111
	v_pk_mul_f32 v[108:109], v[116:117], v[108:109]
	v_pk_mul_f32 v[100:101], v[100:101], v[168:169] op_sel_hi:[1,0]
	v_pk_mul_f32 v[104:105], v[104:105], v[108:109]
	v_pk_mul_f32 v[108:109], v[118:119], v[110:111]
	v_cvt_pk_bf16_f32 v104, v104, v105
	v_pk_mul_f32 v[106:107], v[106:107], v[108:109]
	v_pk_mul_f32 v[102:103], v[102:103], v[168:169] op_sel_hi:[1,0]
	v_cvt_pk_bf16_f32 v105, v106, v107
	v_exp_f32_e32 v106, v100
	v_exp_f32_e32 v107, v101
	v_exp_f32_e32 v108, v102
	v_exp_f32_e32 v109, v103
	v_fma_f32 v106, v106, s99, s99
	v_fma_f32 v107, v107, s99, s99
	v_rcp_f32_e32 v106, v106
	v_rcp_f32_e32 v107, v107
	v_fma_f32 v108, v108, s99, s99
	v_fma_f32 v109, v109, s99, s99
	v_rcp_f32_e32 v108, v108
	v_rcp_f32_e32 v109, v109
	v_pk_mul_f32 v[92:93], v[92:93], v[168:169] op_sel_hi:[1,0]
	v_pk_mul_f32 v[100:101], v[100:101], v[106:107]
	v_pk_mul_f32 v[94:95], v[94:95], v[168:169] op_sel_hi:[1,0]
	v_pk_mul_f32 v[92:93], v[92:93], v[100:101]
	v_pk_mul_f32 v[100:101], v[102:103], v[108:109]
	v_cvt_pk_bf16_f32 v106, v92, v93
	v_pk_mul_f32 v[94:95], v[94:95], v[100:101]
	v_mad_i64_i32 v[92:93], s[24:25], v156, s55, v[140:141]
	v_cvt_pk_bf16_f32 v107, v94, v95
	v_lshl_add_u64 v[92:93], v[92:93], 0, v[142:143]
	global_store_dwordx4 v[92:93], v[104:107], off
	v_pk_mul_f32 v[92:93], v[98:99], v[170:171] op_sel_hi:[1,0]
; DI u32x2 pk4(f32x4 v) { u32x2 r; r.x = pk2(v[0], v[1]); r.y = pk2(v[2], v[3]); return r; }
; DI float silu_f(float x) { return x * __builtin_amdgcn_rcpf(1.f + __builtin_amdgcn_exp2f(-1.4426950409f * x)); }
; #define ROWS8 _Pragma("unroll") for (int ai = 0; ai < 2; ++ai) _Pragma("unroll") for (int m = 0; m < 4; ++m) if (ai == 0 || !hf)
;     DI void operator()(const Acc& acc, const Unit& u, int wr, int wc, int fr, int fq) const {
;     ...
;             ROWS8 { const int r = row0 + ai * HALF + m * 16; const float rs = rsv[ai][m];
;                 u32x4 w;
; #pragma unroll
;                 for (int bj = 0; bj < 2; ++bj) { const f32x4 g = acc[ai][bj][m][0] * rs, uu = acc[ai][bj][m][1] * rs;
;                     f32x4 a; a[0] = silu_f(g[0]) * uu[0]; a[1] = silu_f(g[1]) * uu[1]; a[2] = silu_f(g[2]) * uu[2]; a[3] = silu_f(g[3]) * uu[3];
;                     const u32x2 h = pk4(a); if (bj == 0) { w.x = h.x; w.y = h.y; } else { w.z = h.x; w.w = h.y; } }
;                 *(u32x4*)(WSB(OFF_ACT) + (size_t)r * DFF + ac0) = w;
	v_pk_mul_f32 v[94:95], v[96:97], v[170:171] op_sel_hi:[1,0]
	v_exp_f32_e32 v96, v94
	v_exp_f32_e32 v97, v95
	v_exp_f32_e32 v98, v92
	v_exp_f32_e32 v99, v93
	v_fma_f32 v96, v96, s99, s99
	v_fma_f32 v97, v97, s99, s99
	v_fma_f32 v98, v98, s99, s99
	v_fma_f32 v99, v99, s99, s99
	v_rcp_f32_e32 v96, v96
	v_rcp_f32_e32 v97, v97
	v_rcp_f32_e32 v98, v98
	v_rcp_f32_e32 v99, v99
	v_pk_mul_f32 v[90:91], v[90:91], v[170:171] op_sel_hi:[1,0]
	v_pk_mul_f32 v[88:89], v[88:89], v[170:171] op_sel_hi:[1,0]
	v_pk_mul_f32 v[94:95], v[94:95], v[96:97]
	v_pk_mul_f32 v[92:93], v[92:93], v[98:99]
	v_pk_mul_f32 v[88:89], v[88:89], v[94:95]
	v_pk_mul_f32 v[90:91], v[90:91], v[92:93]
	v_pk_mul_f32 v[84:85], v[84:85], v[170:171] op_sel_hi:[1,0]
	v_cvt_pk_bf16_f32 v88, v88, v89
	v_cvt_pk_bf16_f32 v89, v90, v91
	v_pk_mul_f32 v[86:87], v[86:87], v[170:171] op_sel_hi:[1,0]
	v_exp_f32_e32 v90, v84
	v_exp_f32_e32 v91, v85
	v_exp_f32_e32 v92, v86
	v_exp_f32_e32 v93, v87
	v_fma_f32 v90, v90, s99, s99
	v_fma_f32 v91, v91, s99, s99
	v_rcp_f32_e32 v90, v90
	v_rcp_f32_e32 v91, v91
	v_fma_f32 v92, v92, s99, s99
	v_fma_f32 v93, v93, s99, s99
	v_rcp_f32_e32 v92, v92
	v_rcp_f32_e32 v93, v93
	v_fmamk_f32 v154, v154, 0x3a000000, v163
	v_rsq_f32_e32 v154, v154
	s_nop 0
	v_mul_f32_e32 v154, 0xbfb8aa3b, v154
	v_pk_mul_f32 v[76:77], v[76:77], v[170:171] op_sel_hi:[1,0]
	v_pk_mul_f32 v[84:85], v[84:85], v[90:91]
	v_pk_mul_f32 v[78:79], v[78:79], v[170:171] op_sel_hi:[1,0]
	v_pk_mul_f32 v[76:77], v[76:77], v[84:85]
	v_pk_mul_f32 v[84:85], v[86:87], v[92:93]
	v_cvt_pk_bf16_f32 v90, v76, v77
	v_pk_mul_f32 v[78:79], v[78:79], v[84:85]
	v_mad_i64_i32 v[76:77], s[24:25], v152, s55, v[140:141]
	v_cvt_pk_bf16_f32 v91, v78, v79
	v_lshl_add_u64 v[76:77], v[76:77], 0, v[142:143]
	global_store_dwordx4 v[76:77], v[88:91], off
	v_pk_mul_f32 v[76:77], v[82:83], v[154:155] op_sel_hi:[1,0]
	v_pk_mul_f32 v[78:79], v[80:81], v[154:155] op_sel_hi:[1,0]
	v_exp_f32_e32 v80, v78
	v_exp_f32_e32 v81, v79
	v_exp_f32_e32 v82, v76
	v_exp_f32_e32 v83, v77
	v_fma_f32 v80, v80, s99, s99
	v_fma_f32 v81, v81, s99, s99
	v_fma_f32 v82, v82, s99, s99
	v_fma_f32 v83, v83, s99, s99
	v_rcp_f32_e32 v80, v80
	v_rcp_f32_e32 v81, v81
	v_rcp_f32_e32 v82, v82
	v_rcp_f32_e32 v83, v83
	v_pk_mul_f32 v[74:75], v[74:75], v[154:155] op_sel_hi:[1,0]
	v_pk_mul_f32 v[72:73], v[72:73], v[154:155] op_sel_hi:[1,0]
	v_pk_mul_f32 v[78:79], v[78:79], v[80:81]
	v_pk_mul_f32 v[76:77], v[76:77], v[82:83]
	v_pk_mul_f32 v[72:73], v[72:73], v[78:79]
	v_pk_mul_f32 v[74:75], v[74:75], v[76:77]
	v_pk_mul_f32 v[68:69], v[68:69], v[154:155] op_sel_hi:[1,0]
	v_cvt_pk_bf16_f32 v72, v72, v73
	v_cvt_pk_bf16_f32 v73, v74, v75
	v_pk_mul_f32 v[70:71], v[70:71], v[154:155] op_sel_hi:[1,0]
	v_exp_f32_e32 v74, v68
	v_exp_f32_e32 v75, v69
	v_exp_f32_e32 v76, v70
	v_exp_f32_e32 v77, v71
	v_fma_f32 v74, v74, s99, s99
	v_fma_f32 v75, v75, s99, s99
	v_rcp_f32_e32 v74, v74
	v_rcp_f32_e32 v75, v75
	v_fma_f32 v76, v76, s99, s99
	v_fma_f32 v77, v77, s99, s99
	v_rcp_f32_e32 v76, v76
	v_rcp_f32_e32 v77, v77
	v_pk_mul_f32 v[64:65], v[64:65], v[154:155] op_sel_hi:[1,0]
	v_pk_mul_f32 v[68:69], v[68:69], v[74:75]
	v_pk_mul_f32 v[66:67], v[66:67], v[154:155] op_sel_hi:[1,0]
	v_pk_mul_f32 v[64:65], v[64:65], v[68:69]
	v_pk_mul_f32 v[68:69], v[70:71], v[76:77]
	v_cvt_pk_bf16_f32 v74, v64, v65
	v_pk_mul_f32 v[66:67], v[66:67], v[68:69]
	v_mad_i64_i32 v[64:65], s[24:25], v150, s55, v[140:141]
	v_cvt_pk_bf16_f32 v75, v66, v67
	v_fmamk_f32 v66, v139, 0x3a000000, v163
	v_rsq_f32_e32 v68, v66
	s_nop 0
	v_mul_f32_e32 v68, 0xbfb8aa3b, v68
	v_lshl_add_u64 v[64:65], v[64:65], 0, v[142:143]
	global_store_dwordx4 v[64:65], v[72:75], off
	v_fmamk_f32 v65, v147, 0x3a000000, v163
	v_rsq_f32_e32 v66, v65
	s_nop 0
	v_mul_f32_e32 v66, 0xbfb8aa3b, v66
	v_fmamk_f32 v65, v145, 0x3a000000, v163
	v_pk_mul_f32 v[60:61], v[60:61], v[68:69] op_sel_hi:[1,0]
	v_rsq_f32_e32 v70, v65
	s_nop 0
	v_mul_f32_e32 v70, 0xbfb8aa3b, v70
	v_exp_f32_e32 v65, v60
	v_exp_f32_e32 v67, v61
	v_pk_mul_f32 v[62:63], v[62:63], v[68:69] op_sel_hi:[1,0]
	v_fma_f32 v65, v65, s99, s99
	v_rcp_f32_e32 v72, v65
	v_fma_f32 v65, v67, s99, s99
	v_pk_mul_f32 v[58:59], v[58:59], v[68:69] op_sel_hi:[1,0]
	v_exp_f32_e32 v67, v62
	v_exp_f32_e32 v69, v63
	v_rcp_f32_e32 v73, v65
	v_fma_f32 v65, v67, s99, s99
	v_rcp_f32_e32 v74, v65
	v_fma_f32 v65, v69, s99, s99
	v_rcp_f32_e32 v75, v65
	v_pk_mul_f32 v[56:57], v[56:57], v[68:69] op_sel_hi:[1,0]
	v_pk_mul_f32 v[60:61], v[60:61], v[72:73]
	v_pk_mul_f32 v[52:53], v[52:53], v[68:69] op_sel_hi:[1,0]
	v_pk_mul_f32 v[56:57], v[56:57], v[60:61]
	v_pk_mul_f32 v[60:61], v[62:63], v[74:75]
	v_cvt_pk_bf16_f32 v56, v56, v57
	v_pk_mul_f32 v[58:59], v[58:59], v[60:61]
	v_pk_mul_f32 v[54:55], v[54:55], v[68:69] op_sel_hi:[1,0]
	v_cvt_pk_bf16_f32 v57, v58, v59
	v_exp_f32_e32 v58, v52
	v_exp_f32_e32 v59, v53
	v_exp_f32_e32 v60, v54
	v_exp_f32_e32 v61, v55
	v_fma_f32 v58, v58, s99, s99
	v_fma_f32 v59, v59, s99, s99
	v_rcp_f32_e32 v58, v58
	v_rcp_f32_e32 v59, v59
	v_fma_f32 v60, v60, s99, s99
	v_fma_f32 v61, v61, s99, s99
	v_rcp_f32_e32 v60, v60
	v_rcp_f32_e32 v61, v61
	v_pk_mul_f32 v[44:45], v[44:45], v[68:69] op_sel_hi:[1,0]
	v_pk_mul_f32 v[52:53], v[52:53], v[58:59]
	v_pk_mul_f32 v[46:47], v[46:47], v[68:69] op_sel_hi:[1,0]
	v_pk_mul_f32 v[44:45], v[44:45], v[52:53]
	v_pk_mul_f32 v[52:53], v[54:55], v[60:61]
	v_cvt_pk_bf16_f32 v58, v44, v45
	v_pk_mul_f32 v[46:47], v[46:47], v[52:53]
	v_mad_i64_i32 v[44:45], s[24:25], v148, s55, v[140:141]
; DI u32x2 pk4(f32x4 v) { u32x2 r; r.x = pk2(v[0], v[1]); r.y = pk2(v[2], v[3]); return r; }
; DI float silu_f(float x) { return x * __builtin_amdgcn_rcpf(1.f + __builtin_amdgcn_exp2f(-1.4426950409f * x)); }
; #define ROWS8 _Pragma("unroll") for (int ai = 0; ai < 2; ++ai) _Pragma("unroll") for (int m = 0; m < 4; ++m) if (ai == 0 || !hf)
;     DI void operator()(const Acc& acc, const Unit& u, int wr, int wc, int fr, int fq) const {
;     ...
;             ROWS8 { const int r = row0 + ai * HALF + m * 16; const float rs = rsv[ai][m];
;                 u32x4 w;
; #pragma unroll
;                 for (int bj = 0; bj < 2; ++bj) { const f32x4 g = acc[ai][bj][m][0] * rs, uu = acc[ai][bj][m][1] * rs;
;                     f32x4 a; a[0] = silu_f(g[0]) * uu[0]; a[1] = silu_f(g[1]) * uu[1]; a[2] = silu_f(g[2]) * uu[2]; a[3] = silu_f(g[3]) * uu[3];
;                     const u32x2 h = pk4(a); if (bj == 0) { w.x = h.x; w.y = h.y; } else { w.z = h.x; w.w = h.y; } }
;                 *(u32x4*)(WSB(OFF_ACT) + (size_t)r * DFF + ac0) = w;
	v_cvt_pk_bf16_f32 v59, v46, v47
	v_lshl_add_u64 v[44:45], v[44:45], 0, v[142:143]
	global_store_dwordx4 v[44:45], v[56:59], off
	v_pk_mul_f32 v[44:45], v[50:51], v[70:71] op_sel_hi:[1,0]
	v_pk_mul_f32 v[46:47], v[48:49], v[70:71] op_sel_hi:[1,0]
	v_exp_f32_e32 v48, v46
	v_exp_f32_e32 v49, v47
	v_exp_f32_e32 v50, v44
	v_exp_f32_e32 v51, v45
	v_fma_f32 v48, v48, s99, s99
	v_fma_f32 v49, v49, s99, s99
	v_fma_f32 v50, v50, s99, s99
	v_fma_f32 v51, v51, s99, s99
	v_rcp_f32_e32 v48, v48
	v_rcp_f32_e32 v49, v49
	v_rcp_f32_e32 v50, v50
	v_rcp_f32_e32 v51, v51
	v_pk_mul_f32 v[42:43], v[42:43], v[70:71] op_sel_hi:[1,0]
	v_pk_mul_f32 v[40:41], v[40:41], v[70:71] op_sel_hi:[1,0]
	v_pk_mul_f32 v[46:47], v[46:47], v[48:49]
	v_pk_mul_f32 v[44:45], v[44:45], v[50:51]
	v_pk_mul_f32 v[40:41], v[40:41], v[46:47]
	v_pk_mul_f32 v[42:43], v[42:43], v[44:45]
	v_pk_mul_f32 v[36:37], v[36:37], v[70:71] op_sel_hi:[1,0]
	v_cvt_pk_bf16_f32 v40, v40, v41
	v_cvt_pk_bf16_f32 v41, v42, v43
	v_pk_mul_f32 v[38:39], v[38:39], v[70:71] op_sel_hi:[1,0]
	v_exp_f32_e32 v42, v36
	v_exp_f32_e32 v43, v37
	v_exp_f32_e32 v44, v38
	v_exp_f32_e32 v45, v39
	v_fma_f32 v42, v42, s99, s99
	v_fma_f32 v43, v43, s99, s99
	v_rcp_f32_e32 v42, v42
	v_rcp_f32_e32 v43, v43
	v_fma_f32 v44, v44, s99, s99
	v_fma_f32 v45, v45, s99, s99
	v_rcp_f32_e32 v44, v44
	v_rcp_f32_e32 v45, v45
	v_pk_mul_f32 v[28:29], v[28:29], v[70:71] op_sel_hi:[1,0]
	v_pk_mul_f32 v[36:37], v[36:37], v[42:43]
	v_pk_mul_f32 v[30:31], v[30:31], v[70:71] op_sel_hi:[1,0]
	v_pk_mul_f32 v[28:29], v[28:29], v[36:37]
	v_pk_mul_f32 v[36:37], v[38:39], v[44:45]
	v_cvt_pk_bf16_f32 v42, v28, v29
	v_pk_mul_f32 v[30:31], v[30:31], v[36:37]
	v_mad_i64_i32 v[28:29], s[24:25], v146, s55, v[140:141]
	v_cvt_pk_bf16_f32 v43, v30, v31
	v_lshl_add_u64 v[28:29], v[28:29], 0, v[142:143]
	global_store_dwordx4 v[28:29], v[40:43], off
	v_pk_mul_f32 v[28:29], v[34:35], v[66:67] op_sel_hi:[1,0]
	v_pk_mul_f32 v[30:31], v[32:33], v[66:67] op_sel_hi:[1,0]
	v_exp_f32_e32 v32, v30
	v_exp_f32_e32 v33, v31
	v_exp_f32_e32 v34, v28
	v_exp_f32_e32 v35, v29
	v_fma_f32 v32, v32, s99, s99
	v_fma_f32 v33, v33, s99, s99
	v_fma_f32 v34, v34, s99, s99
	v_fma_f32 v35, v35, s99, s99
	v_rcp_f32_e32 v32, v32
	v_rcp_f32_e32 v33, v33
	v_rcp_f32_e32 v34, v34
	v_rcp_f32_e32 v35, v35
	v_pk_mul_f32 v[26:27], v[26:27], v[66:67] op_sel_hi:[1,0]
	v_pk_mul_f32 v[24:25], v[24:25], v[66:67] op_sel_hi:[1,0]
	v_pk_mul_f32 v[30:31], v[30:31], v[32:33]
	v_pk_mul_f32 v[28:29], v[28:29], v[34:35]
	v_pk_mul_f32 v[24:25], v[24:25], v[30:31]
	v_pk_mul_f32 v[26:27], v[26:27], v[28:29]
	v_pk_mul_f32 v[20:21], v[20:21], v[66:67] op_sel_hi:[1,0]
	v_cvt_pk_bf16_f32 v24, v24, v25
	v_cvt_pk_bf16_f32 v25, v26, v27
	v_pk_mul_f32 v[22:23], v[22:23], v[66:67] op_sel_hi:[1,0]
	v_exp_f32_e32 v26, v20
	v_exp_f32_e32 v27, v21
	v_exp_f32_e32 v28, v22
	v_exp_f32_e32 v29, v23
	v_fma_f32 v26, v26, s99, s99
	v_fma_f32 v27, v27, s99, s99
	v_rcp_f32_e32 v26, v26
	v_rcp_f32_e32 v27, v27
	v_fma_f32 v28, v28, s99, s99
	v_fma_f32 v29, v29, s99, s99
	v_rcp_f32_e32 v28, v28
	v_rcp_f32_e32 v29, v29
	v_fmamk_f32 v64, v149, 0x3a000000, v163
	v_rsq_f32_e32 v64, v64
	s_nop 0
	v_mul_f32_e32 v64, 0xbfb8aa3b, v64
	v_pk_mul_f32 v[12:13], v[12:13], v[66:67] op_sel_hi:[1,0]
	v_pk_mul_f32 v[20:21], v[20:21], v[26:27]
	v_pk_mul_f32 v[14:15], v[14:15], v[66:67] op_sel_hi:[1,0]
	v_pk_mul_f32 v[12:13], v[12:13], v[20:21]
	v_pk_mul_f32 v[20:21], v[22:23], v[28:29]
	v_cvt_pk_bf16_f32 v26, v12, v13
	v_pk_mul_f32 v[14:15], v[14:15], v[20:21]
	v_mad_i64_i32 v[12:13], s[24:25], v144, s55, v[140:141]
	v_cvt_pk_bf16_f32 v27, v14, v15
	v_lshl_add_u64 v[12:13], v[12:13], 0, v[142:143]
	global_store_dwordx4 v[12:13], v[24:27], off
	v_pk_mul_f32 v[12:13], v[18:19], v[64:65] op_sel_hi:[1,0]
	v_pk_mul_f32 v[14:15], v[16:17], v[64:65] op_sel_hi:[1,0]
	v_exp_f32_e32 v16, v14
	v_exp_f32_e32 v17, v15
	v_exp_f32_e32 v18, v12
	v_exp_f32_e32 v19, v13
	v_fma_f32 v16, v16, s99, s99
	v_fma_f32 v17, v17, s99, s99
	v_fma_f32 v18, v18, s99, s99
	v_fma_f32 v19, v19, s99, s99
	v_rcp_f32_e32 v16, v16
	v_rcp_f32_e32 v17, v17
	v_rcp_f32_e32 v18, v18
	v_rcp_f32_e32 v19, v19
	v_pk_mul_f32 v[10:11], v[10:11], v[64:65] op_sel_hi:[1,0]
	v_pk_mul_f32 v[8:9], v[8:9], v[64:65] op_sel_hi:[1,0]
	v_pk_mul_f32 v[14:15], v[14:15], v[16:17]
	v_pk_mul_f32 v[12:13], v[12:13], v[18:19]
	v_pk_mul_f32 v[8:9], v[8:9], v[14:15]
	v_pk_mul_f32 v[10:11], v[10:11], v[12:13]
	v_pk_mul_f32 v[4:5], v[4:5], v[64:65] op_sel_hi:[1,0]
	v_cvt_pk_bf16_f32 v8, v8, v9
	v_cvt_pk_bf16_f32 v9, v10, v11
	v_pk_mul_f32 v[6:7], v[6:7], v[64:65] op_sel_hi:[1,0]
	v_exp_f32_e32 v10, v4
	v_exp_f32_e32 v11, v5
	v_exp_f32_e32 v12, v6
	v_exp_f32_e32 v13, v7
	v_fma_f32 v10, v10, s99, s99
	v_fma_f32 v11, v11, s99, s99
	v_rcp_f32_e32 v10, v10
	v_rcp_f32_e32 v11, v11
	v_fma_f32 v12, v12, s99, s99
	v_fma_f32 v13, v13, s99, s99
	v_rcp_f32_e32 v12, v12
	v_rcp_f32_e32 v13, v13
	v_pk_mul_f32 v[0:1], v[0:1], v[64:65] op_sel_hi:[1,0]
	v_pk_mul_f32 v[4:5], v[4:5], v[10:11]
	v_pk_mul_f32 v[2:3], v[2:3], v[64:65] op_sel_hi:[1,0]
	v_pk_mul_f32 v[0:1], v[0:1], v[4:5]
	v_pk_mul_f32 v[4:5], v[6:7], v[12:13]
	v_cvt_pk_bf16_f32 v10, v0, v1
	v_pk_mul_f32 v[2:3], v[2:3], v[4:5]
	v_mad_i64_i32 v[0:1], s[24:25], v138, s55, v[140:141]
	v_cvt_pk_bf16_f32 v11, v2, v3
	v_lshl_add_u64 v[0:1], v[0:1], 0, v[142:143]
	global_store_dwordx4 v[0:1], v[8:11], off
	s_cbranch_vccz .LBB0_1257
	s_waitcnt vmcnt(0)
	s_cmpk_gt_u32 s88, 0xff
	s_cbranch_scc1 .LBB0_1264
	s_barrier
